# v5 plus NA stagger: waves 4-7 run a copy of the NA unit loop that issues the LDS staging writes at the start of each stage, waves 0-3 keep them at the end
# speedup vs baseline: 1.0079x; 1.0079x over previous
; #define LAS __attribute__((address_space(3)))
; __device__ __forceinline__ void na_attn_block(LAS unsigned char* lds, rsrc_t R, int l, int bx, int G, int tid, int lane, int wave) {
;     const int n = lane & 15, kq = lane >> 4, qg = wave & 3, hsel = wave >> 2;
;     const int kc0 = (qg == 0) ? 0 : (qg == 1 ? 8 : (qg == 2 ? 24 : 32));
;     const int qcol = 16 * qg + n; int cs = qcol - 8; cs = cs < 0 ? 0 : (cs > 48 ? 48 : cs);
;     for (int i = tid; i < 8 * 15 * 31; i += NWAVES * 64) *(LAS float*)(lds + NA_RPB + i * 4) = bld<float>(R, (unsigned)i * 4u, OFF_RPB + (unsigned)(l * 8 * 15 * 31) * 4u);
;     const unsigned co = (unsigned)tid * 16u;
;     int kfb = hsel * 16384 + ((kc0 >> 3) + (n >> 3)) * 2048 + kq * 128 + (n & 7) * 16;
;     int vfb = hsel * 16384 + ((kc0 >> 2) + kq) * 1024 + n * 8;
;     int skb = NA_SSK + (hsel * 64 + kc0 + 4 * kq) * 4;
;     asm volatile("" : "+v"(kfb), "+v"(vfb), "+v"(skb));
;     const unsigned qo = (unsigned)(n * PROJ_W + 8 * kq) * 2u, yo = (unsigned)(n * DM + 4 * kq) * 2u;
;     const unsigned gqk_off = OFF_GQK + (unsigned)((l * 2 + 0) * HD) * 4u;
;     f32x4 gq[4][2];
; #pragma unroll
;     for (int ks = 0; ks < 4; ++ks) { gq[ks][0] = bld<f32x4>(R, (unsigned)kq * 32u, gqk_off + 128 * ks); gq[ks][1] = bld<f32x4>(R, (unsigned)kq * 32u, gqk_off + 128 * ks + 16); }
;     ...
;               for (int q = 0; q < 8; ++q) { const int kcol = kc0 + 16 * (q >> 2) + 4 * kq + (q & 3); const bool valid = (kcol >= cs) && (kcol < cs + 16);
;                   int ci = kcol - qcol + 15; ci = ci < 0 ? 0 : (ci > 30 ? 30 : ci);
.LBB0_182:
	s_or_b64 exec, exec, s[0:1]
	s_lshr_b32 s0, s5, 3
	v_lshrrev_b32_e32 v0, 3, v32
	v_add_u32_e32 v0, s0, v0
	v_readlane_b32 s1, v253, 31
	v_lshlrev_b32_e32 v2, 4, v160
	s_waitcnt lgkmcnt(0)
	v_lshlrev_b32_e32 v1, 7, v33
	v_lshl_add_u32 v0, v0, 11, s1
	v_and_b32_e32 v2, 0x70, v2
	s_lshr_b32 s0, s5, 2
	v_or3_b32 v34, v0, v1, v2
	v_add_u32_e32 v0, s0, v33
	v_lshl_add_u32 v0, v0, 10, s1
	v_lshlrev_b32_e32 v37, 2, v33
	v_readlane_b32 s0, v253, 33
	v_lshl_or_b32 v36, v32, 3, v0
	s_nop 0
	v_or_b32_e32 v0, s0, v37
	v_readlane_b32 s0, v253, 34
	v_add_u32_e32 v0, s5, v0
	v_readlane_b32 s1, v253, 35
	v_lshl_add_u32 v35, v0, 2, v221
	s_and_b64 vcc, exec, s[0:1]
	s_cbranch_vccz .LBB0_313
	s_lshl_b32 s0, s8, 10
	s_add_i32 s1, s0, 0x9c0180
	v_lshlrev_b32_e32 v28, 5, v33
	s_or_b32 s2, s1, 16
	s_mov_b32 s40, s34
	s_mov_b32 s41, s93
	s_mov_b32 s42, s94
	s_mov_b32 s43, s95
	buffer_load_dwordx4 v[0:3], v28, s[40:43], s2 offen
	buffer_load_dwordx4 v[4:7], v28, s[40:43], s1 offen
	s_add_i32 s1, s0, 0x9c0100
	s_or_b32 s2, s1, 16
	buffer_load_dwordx4 v[8:11], v28, s[40:43], s2 offen
	buffer_load_dwordx4 v[12:15], v28, s[40:43], s1 offen
	s_add_i32 s1, s0, 0x9c0080
	s_or_b32 s2, s1, 16
	s_add_i32 s0, s0, 0x9c0000
	buffer_load_dwordx4 v[16:19], v28, s[40:43], s2 offen
	buffer_load_dwordx4 v[20:23], v28, s[40:43], s1 offen
	s_or_b32 s1, s0, 16
	buffer_load_dwordx4 v[24:27], v28, s[40:43], s1 offen
	s_nop 0
	buffer_load_dwordx4 v[28:31], v28, s[40:43], s0 offen
	v_and_b32_e32 v41, 64, v220
	v_xor_b32_e32 v40, 16, v220
	v_add_u32_e32 v41, 64, v41
	v_mul_u32_u24_e32 v38, 0x1800, v32
	v_readlane_b32 s0, v253, 30
	v_cmp_lt_i32_e32 vcc, v40, v41
	v_and_or_b32 v232, v161, 48, v38
	v_lshlrev_b32_e32 v38, 12, v32
	v_or_b32_e32 v32, s0, v32
	v_cndmask_b32_e32 v40, v220, v40, vcc
	v_lshl_or_b32 v233, v33, 3, v38
	v_med3_u32 v33, v32, 8, 56
	v_lshlrev_b32_e32 v235, 2, v40
	v_xor_b32_e32 v40, 32, v220
	v_add_u32_e32 v37, s5, v37
	v_add_u32_e32 v38, -8, v33
	s_mul_i32 s0, s8, 20
	v_readlane_b32 s1, v253, 36
	v_cmp_lt_i32_e32 vcc, v40, v41
	v_add_u32_e32 v33, 8, v33
	v_add_u32_e32 v237, 0, v36
	v_sub_u32_e32 v36, v37, v32
	s_or_b32 s4, s0, s1
	v_cndmask_b32_e32 v40, v220, v40, vcc
	v_cmp_ge_u32_e32 vcc, v37, v38
	v_cmp_lt_u32_e64 s[0:1], v37, v33
	v_med3_i32 v238, v36, -15, 15
	v_or_b32_e32 v36, 1, v37
	s_and_b64 s[6:7], vcc, s[0:1]
	v_cmp_ge_u32_e32 vcc, v36, v38
	v_cmp_lt_u32_e64 s[0:1], v36, v33
	v_sub_u32_e32 v36, v36, v32
	v_med3_i32 v239, v36, -15, 15
	v_or_b32_e32 v36, 2, v37
	s_and_b64 s[22:23], vcc, s[0:1]
	v_cmp_ge_u32_e32 vcc, v36, v38
	v_cmp_lt_u32_e64 s[0:1], v36, v33
	v_sub_u32_e32 v36, v36, v32
	v_med3_i32 v240, v36, -15, 15
	v_or_b32_e32 v36, 3, v37
	s_and_b64 s[28:29], vcc, s[0:1]
	v_cmp_ge_u32_e32 vcc, v36, v38
	v_cmp_lt_u32_e64 s[0:1], v36, v33
	v_sub_u32_e32 v36, v36, v32
	v_med3_i32 v241, v36, -15, 15
	v_add_u32_e32 v36, 16, v37
	s_and_b64 s[30:31], vcc, s[0:1]
	v_cmp_ge_u32_e32 vcc, v36, v38
	v_cmp_lt_u32_e64 s[0:1], v36, v33
	v_sub_u32_e32 v36, v36, v32
	v_med3_i32 v242, v36, -15, 15
	v_add_u32_e32 v36, 17, v37
	s_and_b64 s[36:37], vcc, s[0:1]
	v_cmp_ge_u32_e32 vcc, v36, v38
	v_cmp_lt_u32_e64 s[0:1], v36, v33
	v_sub_u32_e32 v36, v36, v32
	v_med3_i32 v243, v36, -15, 15
	v_add_u32_e32 v36, 18, v37
	s_and_b64 s[38:39], vcc, s[0:1]
	v_cmp_ge_u32_e32 vcc, v36, v38
	v_cmp_lt_u32_e64 s[0:1], v36, v33
	v_sub_u32_e32 v36, v36, v32
	v_med3_i32 v244, v36, -15, 15
	v_add_u32_e32 v36, 19, v37
	v_lshlrev_b32_e32 v39, 2, v162
	v_sub_u32_e32 v32, v36, v32
	s_and_b64 s[44:45], vcc, s[0:1]
	v_cmp_ge_u32_e32 vcc, v36, v38
	v_cmp_lt_u32_e64 s[0:1], v36, v33
	v_med3_i32 v245, v32, -15, 15
	v_add_u32_e32 v32, 0, v39
	v_lshlrev_b32_e32 v234, 2, v160
	v_lshlrev_b32_e32 v236, 2, v40
	s_and_b64 s[0:1], vcc, s[0:1]
	s_lshl_b32 s5, s86, 1
	v_add_u32_e32 v246, 0x10000, v32
	v_add_u32_e32 v247, 0, v34
	v_add_u32_e32 v248, 0, v35
	v_readlane_b32 s10, v252, 44
	s_mov_b32 s11, s99
	s_cmp_lt_u32 s77, 4
	s_cbranch_scc1 .LBB0_185
	s_branch .Lna2_185

; __device__ __forceinline__ float max_fq(float v) { v = fmaxf(v, __shfl_xor(v, 16)); v = fmaxf(v, __shfl_xor(v, 32)); return v; }
; __device__ __forceinline__ void na_attn_block(LAS unsigned char* lds, rsrc_t R, int l, int bx, int G, int tid, int lane, int wave) {
;     ...
;         float mx = -3e38f;
; #pragma unroll
;         for (int a = 0; a < 8; ++a)
; #pragma unroll
;             for (int t = 0; t < 2; ++t)
; #pragma unroll
;                 for (int j = 0; j < 4; ++j) mx = fmaxf(mx, S[a][t][j]);
;         mx = pg8::max_fq(mx);
;         float sum = 0.f;
; #pragma unroll
;         for (int a = 0; a < 8; ++a) {
; #pragma unroll
;             for (int t = 0; t < 2; ++t)
; #pragma unroll
;                 for (int j = 0; j < 4; ++j) { const float p = __expf(S[a][t][j] - mx); S[a][t][j] = p; sum += p; }
.Lna2_184:
	s_or_b64 exec, exec, s[2:3]
	v_max3_f32 v66, v189, s79, v188
	v_max3_f32 v66, v66, v191, v190
	v_max3_f32 v66, v66, v177, v176
	v_max3_f32 v66, v66, v179, v178
	v_max3_f32 v66, v66, v165, v164
	v_max3_f32 v66, v66, v167, v166
	v_max3_f32 v66, v66, v169, v168
	v_max3_f32 v66, v66, v171, v170
	v_max3_f32 v66, v66, v149, v148
	v_max3_f32 v66, v66, v151, v150
	v_max3_f32 v66, v66, v153, v152
	v_max3_f32 v66, v66, v155, v154
	v_max3_f32 v66, v66, v129, v128
	v_max3_f32 v66, v66, v131, v130
	v_max3_f32 v66, v66, v133, v132
	v_max3_f32 v66, v66, v135, v134
	v_max3_f32 v66, v66, v117, v116
	v_max3_f32 v66, v66, v119, v118
	v_max3_f32 v66, v66, v113, v112
	v_max3_f32 v66, v66, v107, v106
	v_max3_f32 v66, v66, v97, v96
	v_max3_f32 v66, v66, v99, v98
	v_max3_f32 v66, v66, v105, v100
	v_max3_f32 v66, v66, v95, v94
	v_max3_f32 v66, v66, v77, v76
	v_max3_f32 v66, v66, v79, v78
	v_max3_f32 v66, v66, v81, v80
	v_max3_f32 v66, v66, v83, v82
	v_max3_f32 v66, v66, v85, v84
	v_max3_f32 v66, v66, v75, v74
	v_max3_f32 v66, v66, v69, v68
	v_max3_f32 v66, v66, v65, v64
	ds_bpermute_b32 v67, v235, v66
	s_waitcnt lgkmcnt(0)
	v_max_f32_e32 v67, v67, v67
	v_max_f32_e32 v66, v66, v67
	ds_bpermute_b32 v67, v236, v66
	s_waitcnt lgkmcnt(0)
	v_max_f32_e32 v67, v67, v67
	v_max_f32_e32 v66, v66, v67
	v_sub_f32_e32 v67, v189, v66
	v_sub_f32_e32 v70, v188, v66
	v_mul_f32_e32 v67, 0x3fb8aa3b, v67
	v_sub_f32_e32 v71, v191, v66
	v_mul_f32_e32 v70, 0x3fb8aa3b, v70
	v_exp_f32_e32 v139, v67
	v_sub_f32_e32 v72, v190, v66
	v_mul_f32_e32 v71, 0x3fb8aa3b, v71
	v_exp_f32_e32 v140, v70
	v_sub_f32_e32 v70, v176, v66
	v_sub_f32_e32 v73, v177, v66
	v_mul_f32_e32 v72, 0x3fb8aa3b, v72
	v_exp_f32_e32 v141, v71
	v_mul_f32_e32 v70, 0x3fb8aa3b, v70
	v_mul_f32_e32 v73, 0x3fb8aa3b, v73
	v_exp_f32_e32 v142, v72
	v_exp_f32_e32 v144, v70
	v_sub_f32_e32 v70, v179, v66
	v_add_f32_e32 v67, 0, v139
	v_exp_f32_e32 v143, v73
	v_mul_f32_e32 v70, 0x3fb8aa3b, v70
	v_add_f32_e32 v67, v140, v67
	v_exp_f32_e32 v145, v70
	v_sub_f32_e32 v70, v178, v66
	v_add_f32_e32 v67, v141, v67
	v_mul_f32_e32 v70, 0x3fb8aa3b, v70
	v_add_f32_e32 v67, v142, v67
	v_exp_f32_e32 v146, v70
	v_add_f32_e32 v67, v143, v67
	v_add_f32_e32 v67, v144, v67
	v_add_f32_e32 v67, v145, v67
	v_add_f32_e32 v67, v146, v67
	v_sub_f32_e32 v70, v165, v66
	v_mul_f32_e32 v70, 0x3fb8aa3b, v70
	v_exp_f32_e32 v172, v70
	v_sub_f32_e32 v70, v164, v66
	v_mul_f32_e32 v70, 0x3fb8aa3b, v70
	v_exp_f32_e32 v173, v70
	v_sub_f32_e32 v70, v167, v66
	v_mul_f32_e32 v70, 0x3fb8aa3b, v70
	v_exp_f32_e32 v174, v70
	v_sub_f32_e32 v70, v166, v66
	v_mul_f32_e32 v70, 0x3fb8aa3b, v70
	v_exp_f32_e32 v175, v70
	v_sub_f32_e32 v70, v169, v66
	v_mul_f32_e32 v70, 0x3fb8aa3b, v70
	v_exp_f32_e32 v176, v70
	v_sub_f32_e32 v70, v168, v66
	v_mul_f32_e32 v70, 0x3fb8aa3b, v70
	v_exp_f32_e32 v177, v70
	v_sub_f32_e32 v70, v171, v66
	v_add_f32_e32 v67, v172, v67
	v_mul_f32_e32 v70, 0x3fb8aa3b, v70
	v_add_f32_e32 v67, v173, v67
	v_exp_f32_e32 v178, v70
	v_sub_f32_e32 v70, v170, v66
	v_add_f32_e32 v67, v174, v67
	v_mul_f32_e32 v70, 0x3fb8aa3b, v70
	v_add_f32_e32 v67, v175, v67
	v_exp_f32_e32 v179, v70
	v_add_f32_e32 v67, v176, v67
	v_add_f32_e32 v67, v177, v67
	v_add_f32_e32 v67, v178, v67
	v_add_f32_e32 v67, v179, v67
	v_sub_f32_e32 v70, v149, v66
	v_mul_f32_e32 v70, 0x3fb8aa3b, v70
	v_exp_f32_e32 v136, v70
	v_sub_f32_e32 v70, v148, v66
	v_mul_f32_e32 v70, 0x3fb8aa3b, v70
	v_exp_f32_e32 v137, v70
	v_sub_f32_e32 v70, v151, v66
	v_mul_f32_e32 v70, 0x3fb8aa3b, v70
	v_exp_f32_e32 v138, v70
	v_sub_f32_e32 v70, v150, v66
	v_mul_f32_e32 v70, 0x3fb8aa3b, v70
	v_exp_f32_e32 v180, v70
	v_sub_f32_e32 v70, v153, v66
	v_mul_f32_e32 v70, 0x3fb8aa3b, v70
	v_exp_f32_e32 v181, v70
	v_sub_f32_e32 v70, v152, v66
	v_mul_f32_e32 v70, 0x3fb8aa3b, v70
	v_exp_f32_e32 v182, v70
	v_sub_f32_e32 v70, v155, v66
	v_add_f32_e32 v67, v136, v67
	v_mul_f32_e32 v70, 0x3fb8aa3b, v70
	v_add_f32_e32 v67, v137, v67
	v_exp_f32_e32 v183, v70
	v_sub_f32_e32 v70, v154, v66
	v_add_f32_e32 v67, v138, v67
	v_mul_f32_e32 v70, 0x3fb8aa3b, v70
	v_add_f32_e32 v67, v180, v67
	v_exp_f32_e32 v184, v70
	v_add_f32_e32 v67, v181, v67
	v_add_f32_e32 v67, v182, v67
	v_add_f32_e32 v67, v183, v67
	v_add_f32_e32 v67, v184, v67
	v_sub_f32_e32 v70, v129, v66
	v_mul_f32_e32 v70, 0x3fb8aa3b, v70
	v_exp_f32_e32 v120, v70
	v_sub_f32_e32 v70, v128, v66
	v_mul_f32_e32 v70, 0x3fb8aa3b, v70
	v_exp_f32_e32 v121, v70
	v_sub_f32_e32 v70, v131, v66
	v_mul_f32_e32 v70, 0x3fb8aa3b, v70
	v_exp_f32_e32 v122, v70
	v_sub_f32_e32 v70, v130, v66
	v_mul_f32_e32 v70, 0x3fb8aa3b, v70
	v_exp_f32_e32 v123, v70
	v_sub_f32_e32 v70, v133, v66
	v_mul_f32_e32 v70, 0x3fb8aa3b, v70
	v_exp_f32_e32 v124, v70
	v_sub_f32_e32 v70, v132, v66
	v_mul_f32_e32 v70, 0x3fb8aa3b, v70
	v_exp_f32_e32 v125, v70
	v_sub_f32_e32 v70, v135, v66
	v_add_f32_e32 v67, v120, v67
	v_mul_f32_e32 v70, 0x3fb8aa3b, v70
	v_add_f32_e32 v67, v121, v67
	v_exp_f32_e32 v126, v70
	v_sub_f32_e32 v70, v134, v66
	v_add_f32_e32 v67, v122, v67
	v_mul_f32_e32 v70, 0x3fb8aa3b, v70
	v_add_f32_e32 v67, v123, v67
	v_exp_f32_e32 v127, v70
	v_add_f32_e32 v67, v124, v67
	v_add_f32_e32 v67, v125, v67
	v_add_f32_e32 v67, v126, v67
	v_add_f32_e32 v67, v127, v67
	v_sub_f32_e32 v70, v117, v66
	v_mul_f32_e32 v70, 0x3fb8aa3b, v70
	v_exp_f32_e32 v109, v70
	v_sub_f32_e32 v70, v116, v66
	v_mul_f32_e32 v70, 0x3fb8aa3b, v70
	v_exp_f32_e32 v110, v70
	v_sub_f32_e32 v70, v119, v66
	v_mul_f32_e32 v70, 0x3fb8aa3b, v70
	v_exp_f32_e32 v111, v70
	v_sub_f32_e32 v70, v118, v66
	v_mul_f32_e32 v70, 0x3fb8aa3b, v70
	v_exp_f32_e32 v114, v70
	v_sub_f32_e32 v70, v113, v66
	v_mul_f32_e32 v70, 0x3fb8aa3b, v70
	v_exp_f32_e32 v113, v70
	v_sub_f32_e32 v70, v112, v66
; __device__ __forceinline__ u32x4 pack8(const f32x4 v0, const f32x4 v1) { u32x4 w; w.x = cvt_pk_bf16(v0[0], v0[1]); w.y = cvt_pk_bf16(v0[2], v0[3]); w.z = cvt_pk_bf16(v1[0], v1[1]); w.w = cvt_pk_bf16(v1[2], v1[3]); return w; }
; __device__ __forceinline__ float sum_fq(float v) { v += __shfl_xor(v, 16); v += __shfl_xor(v, 32); return v; }
; #define LAS __attribute__((address_space(3)))
; #define MFMA16(a, b, c) __builtin_amdgcn_mfma_f32_16x16x32_bf16((a), (b), (c), 0, 0, 0)
; #define SCHED_FENCE() __builtin_amdgcn_sched_barrier(0)
; #define NA_ISSUE(seq_, slot_) do { _Pragma("unroll") for (int j = 0; j < 4; ++j) st[slot_][j] = bld<u32x4>(R, co, ((seq_) < 8 ? (unsigned)WS_KB + rowb + (unsigned)((seq_) * 131072) : OFF_VT + rowb + (unsigned)(((seq_) - 8) * 131072)) + (unsigned)j * 8192u); } while (0)
; __device__ __forceinline__ void na_attn_block(LAS unsigned char* lds, rsrc_t R, int l, int bx, int G, int tid, int lane, int wave) {
;     ...
;         float sum = 0.f;
; #pragma unroll
;         for (int a = 0; a < 8; ++a) {
; #pragma unroll
;             for (int t = 0; t < 2; ++t)
; #pragma unroll
;                 for (int j = 0; j < 4; ++j) { const float p = __expf(S[a][t][j] - mx); S[a][t][j] = p; sum += p; }
;             SCHED_FENCE();
;         }
;         sum = pg8::sum_fq(sum);
;         f32x4 o[8];
; #pragma unroll
;         for (int dt = 0; dt < 8; ++dt) o[dt] = (f32x4){0.f, 0.f, 0.f, 0.f};
; #pragma unroll
;         for (int a = 0; a < 8; ++a) {
;             if (a + 3 < 8) NA_ISSUE(8 + a + 3, (8 + a) % 3);
;             SCHED_FENCE();
;             const int buf = (a & 1) * NA_BUF;
;             const u32x4 pw = pg8::pack8(S[a][0], S[a][1]); const bf16x8 pf = __builtin_bit_cast(bf16x8, pw);
; #pragma unroll
;             for (int dt = 0; dt < 8; ++dt) { const u32x2 lo = *(const LAS u32x2*)(lds + vfb + buf + dt * 128), hi = *(const LAS u32x2*)(lds + vfb + buf + dt * 128 + 4096);
;                 const u32x4 vw = (u32x4){lo.x, lo.y, hi.x, hi.y}; o[dt] = MFMA16(__builtin_bit_cast(bf16x8, vw), pf, o[dt]); }
	v_mul_f32_e32 v70, 0x3fb8aa3b, v70
	v_exp_f32_e32 v112, v70
	v_sub_f32_e32 v70, v107, v66
	v_add_f32_e32 v67, v109, v67
	v_mul_f32_e32 v70, 0x3fb8aa3b, v70
	v_add_f32_e32 v67, v110, v67
	v_exp_f32_e32 v115, v70
	v_sub_f32_e32 v70, v106, v66
	v_add_f32_e32 v67, v111, v67
	v_mul_f32_e32 v70, 0x3fb8aa3b, v70
	v_add_f32_e32 v67, v114, v67
	v_exp_f32_e32 v116, v70
	v_add_f32_e32 v67, v113, v67
	v_add_f32_e32 v67, v112, v67
	v_add_f32_e32 v67, v115, v67
	v_add_f32_e32 v67, v116, v67
	v_sub_f32_e32 v70, v97, v66
	v_mul_f32_e32 v70, 0x3fb8aa3b, v70
	v_exp_f32_e32 v101, v70
	v_sub_f32_e32 v70, v96, v66
	v_mul_f32_e32 v70, 0x3fb8aa3b, v70
	v_exp_f32_e32 v102, v70
	v_sub_f32_e32 v70, v99, v66
	v_mul_f32_e32 v70, 0x3fb8aa3b, v70
	v_exp_f32_e32 v103, v70
	v_sub_f32_e32 v70, v98, v66
	v_mul_f32_e32 v70, 0x3fb8aa3b, v70
	v_exp_f32_e32 v104, v70
	v_sub_f32_e32 v70, v105, v66
	v_mul_f32_e32 v70, 0x3fb8aa3b, v70
	v_exp_f32_e32 v105, v70
	v_sub_f32_e32 v70, v100, v66
	v_mul_f32_e32 v70, 0x3fb8aa3b, v70
	v_exp_f32_e32 v106, v70
	v_sub_f32_e32 v70, v95, v66
	v_add_f32_e32 v67, v101, v67
	v_mul_f32_e32 v70, 0x3fb8aa3b, v70
	v_add_f32_e32 v67, v102, v67
	v_exp_f32_e32 v107, v70
	v_sub_f32_e32 v70, v94, v66
	v_add_f32_e32 v67, v103, v67
	v_mul_f32_e32 v70, 0x3fb8aa3b, v70
	v_add_f32_e32 v67, v104, v67
	v_exp_f32_e32 v108, v70
	v_add_f32_e32 v67, v105, v67
	v_add_f32_e32 v67, v106, v67
	v_add_f32_e32 v67, v107, v67
	v_add_f32_e32 v67, v108, v67
	v_sub_f32_e32 v70, v77, v66
	v_mul_f32_e32 v70, 0x3fb8aa3b, v70
	v_exp_f32_e32 v90, v70
	v_sub_f32_e32 v70, v76, v66
	v_mul_f32_e32 v70, 0x3fb8aa3b, v70
	v_exp_f32_e32 v91, v70
	v_sub_f32_e32 v70, v79, v66
	v_mul_f32_e32 v70, 0x3fb8aa3b, v70
	v_exp_f32_e32 v92, v70
	v_sub_f32_e32 v70, v78, v66
	v_mul_f32_e32 v70, 0x3fb8aa3b, v70
	v_exp_f32_e32 v93, v70
	v_sub_f32_e32 v70, v81, v66
	v_mul_f32_e32 v70, 0x3fb8aa3b, v70
	v_exp_f32_e32 v94, v70
	v_sub_f32_e32 v70, v80, v66
	v_mul_f32_e32 v70, 0x3fb8aa3b, v70
	v_exp_f32_e32 v95, v70
	v_sub_f32_e32 v70, v83, v66
	v_add_f32_e32 v67, v90, v67
	v_mul_f32_e32 v70, 0x3fb8aa3b, v70
	v_add_f32_e32 v67, v91, v67
	v_exp_f32_e32 v96, v70
	v_sub_f32_e32 v70, v82, v66
	v_add_f32_e32 v67, v92, v67
	v_mul_f32_e32 v70, 0x3fb8aa3b, v70
	v_add_f32_e32 v67, v93, v67
	v_exp_f32_e32 v97, v70
	v_add_f32_e32 v67, v94, v67
	v_add_f32_e32 v67, v95, v67
	v_add_f32_e32 v67, v96, v67
	v_add_f32_e32 v67, v97, v67
	v_sub_f32_e32 v70, v85, v66
	v_mul_f32_e32 v70, 0x3fb8aa3b, v70
	v_exp_f32_e32 v82, v70
	v_sub_f32_e32 v70, v84, v66
	v_mul_f32_e32 v70, 0x3fb8aa3b, v70
	v_exp_f32_e32 v83, v70
	v_sub_f32_e32 v70, v75, v66
	v_mul_f32_e32 v70, 0x3fb8aa3b, v70
	v_exp_f32_e32 v84, v70
	v_sub_f32_e32 v70, v74, v66
	v_mul_f32_e32 v70, 0x3fb8aa3b, v70
	v_sub_f32_e32 v69, v69, v66
	v_exp_f32_e32 v85, v70
	v_mul_f32_e32 v69, 0x3fb8aa3b, v69
	v_sub_f32_e32 v68, v68, v66
	v_add_f32_e32 v67, v82, v67
	v_exp_f32_e32 v86, v69
	v_mul_f32_e32 v68, 0x3fb8aa3b, v68
	v_sub_f32_e32 v65, v65, v66
	v_add_f32_e32 v67, v83, v67
	v_exp_f32_e32 v87, v68
	v_mul_f32_e32 v65, 0x3fb8aa3b, v65
	v_sub_f32_e32 v64, v64, v66
	v_add_f32_e32 v67, v84, v67
	v_exp_f32_e32 v88, v65
	v_mul_f32_e32 v64, 0x3fb8aa3b, v64
	v_add_f32_e32 v67, v85, v67
	v_exp_f32_e32 v89, v64
	v_add_f32_e32 v64, v86, v67
	v_add_f32_e32 v64, v87, v64
	v_add_f32_e32 v64, v88, v64
	v_add_f32_e32 v64, v89, v64
	ds_bpermute_b32 v65, v235, v64
	s_add_i32 s2, s14, 0x20e60000
	s_mov_b32 s92, s34
	s_waitcnt lgkmcnt(0)
	v_add_f32_e32 v80, v64, v65
	buffer_load_dwordx4 v[64:67], v208, s[92:95], s2 offen
	s_add_i32 s2, s14, 0x20e62000
	buffer_load_dwordx4 v[68:71], v208, s[92:95], s2 offen
	s_add_i32 s2, s14, 0x20e64000
	buffer_load_dwordx4 v[72:75], v208, s[92:95], s2 offen
	s_add_i32 s2, s14, 0x20e66000
	buffer_load_dwordx4 v[76:79], v208, s[92:95], s2 offen
	ds_bpermute_b32 v81, v236, v80
	v_add_u32_e32 v98, 0x1000, v237
	v_cvt_pk_bf16_f32 v128, v139, v140
	v_cvt_pk_bf16_f32 v129, v141, v142
	v_cvt_pk_bf16_f32 v130, v143, v144
	v_cvt_pk_bf16_f32 v131, v145, v146
	ds_read2_b64 v[132:135], v237 offset1:16
	ds_read2_b64 v[140:143], v98 offset1:16
	s_waitcnt lgkmcnt(1)
	v_mov_b32_e32 v144, v132
	v_mov_b32_e32 v145, v133
	s_waitcnt lgkmcnt(0)
	v_mov_b32_e32 v146, v140
	v_mov_b32_e32 v147, v141
	v_mov_b32_e32 v140, v134
	v_mov_b32_e32 v141, v135
	ds_read2_b64 v[132:135], v237 offset0:32 offset1:48
	ds_read2_b64 v[148:151], v98 offset0:32 offset1:48
	v_mfma_f32_16x16x32_bf16 v[144:147], v[144:147], v[128:131], 0
	s_waitcnt lgkmcnt(1)
	v_mov_b32_e32 v152, v132
	v_mov_b32_e32 v153, v133
	s_waitcnt lgkmcnt(0)
	v_mov_b32_e32 v154, v148
	v_mov_b32_e32 v155, v149
	v_mov_b32_e32 v148, v134
	v_mov_b32_e32 v149, v135
	ds_read2_b64 v[132:135], v237 offset0:64 offset1:80
	ds_read2_b64 v[156:159], v98 offset0:64 offset1:80
	v_mfma_f32_16x16x32_bf16 v[140:143], v[140:143], v[128:131], 0
	s_waitcnt lgkmcnt(1)
	v_mov_b32_e32 v160, v132
	v_mov_b32_e32 v161, v133
	s_waitcnt lgkmcnt(0)
	v_mov_b32_e32 v162, v156
	v_mov_b32_e32 v163, v157
	v_mov_b32_e32 v156, v134
	v_mov_b32_e32 v157, v135
	ds_read2_b64 v[132:135], v237 offset0:96 offset1:112
	ds_read2_b64 v[164:167], v98 offset0:96 offset1:112
	v_mfma_f32_16x16x32_bf16 v[152:155], v[152:155], v[128:131], 0
	s_waitcnt lgkmcnt(1)
	v_mov_b32_e32 v168, v132
	v_mov_b32_e32 v169, v133
	s_waitcnt lgkmcnt(0)
	v_mov_b32_e32 v170, v164
	v_mov_b32_e32 v171, v165
	v_mov_b32_e32 v164, v134
	v_mov_b32_e32 v165, v135
	v_mfma_f32_16x16x32_bf16 v[148:151], v[148:151], v[128:131], 0
	v_mfma_f32_16x16x32_bf16 v[160:163], v[160:163], v[128:131], 0
	v_mfma_f32_16x16x32_bf16 v[156:159], v[156:159], v[128:131], 0
	v_mfma_f32_16x16x32_bf16 v[168:171], v[168:171], v[128:131], 0
	v_mfma_f32_16x16x32_bf16 v[128:131], v[164:167], v[128:131], 0
	s_add_i32 s2, s14, 0x20e80000
	s_waitcnt vmcnt(11)
	ds_write_b128 v249, v[32:35] offset:32768
	s_waitcnt vmcnt(10)
	ds_write_b128 v249, v[40:43] offset:40960
	s_waitcnt vmcnt(9)
	ds_write_b128 v249, v[44:47] offset:49152
	s_waitcnt vmcnt(8)
	ds_write_b128 v249, v[56:59] offset:57344
	s_waitcnt lgkmcnt(0)
	s_barrier
; __device__ __forceinline__ u32x4 pack8(const f32x4 v0, const f32x4 v1) { u32x4 w; w.x = cvt_pk_bf16(v0[0], v0[1]); w.y = cvt_pk_bf16(v0[2], v0[3]); w.z = cvt_pk_bf16(v1[0], v1[1]); w.w = cvt_pk_bf16(v1[2], v1[3]); return w; }
; #define LAS __attribute__((address_space(3)))
; #define MFMA16(a, b, c) __builtin_amdgcn_mfma_f32_16x16x32_bf16((a), (b), (c), 0, 0, 0)
; #define SCHED_FENCE() __builtin_amdgcn_sched_barrier(0)
; #define NA_ISSUE(seq_, slot_) do { _Pragma("unroll") for (int j = 0; j < 4; ++j) st[slot_][j] = bld<u32x4>(R, co, ((seq_) < 8 ? (unsigned)WS_KB + rowb + (unsigned)((seq_) * 131072) : OFF_VT + rowb + (unsigned)(((seq_) - 8) * 131072)) + (unsigned)j * 8192u); } while (0)
; #define NA_WRITE(slot_, buf_) do { _Pragma("unroll") for (int j = 0; j < 4; ++j) *(LAS u32x4*)(lds + (buf_) * NA_BUF + j * 8192 + tid * 16) = st[slot_][j]; } while (0)
; __device__ __forceinline__ void na_attn_block(LAS unsigned char* lds, rsrc_t R, int l, int bx, int G, int tid, int lane, int wave) {
;     ...
; #pragma unroll
;         for (int a = 0; a < 8; ++a) {
;             if (a + 3 < 8) NA_ISSUE(8 + a + 3, (8 + a) % 3);
;             SCHED_FENCE();
;             const int buf = (a & 1) * NA_BUF;
;             const u32x4 pw = pg8::pack8(S[a][0], S[a][1]); const bf16x8 pf = __builtin_bit_cast(bf16x8, pw);
; #pragma unroll
;             for (int dt = 0; dt < 8; ++dt) { const u32x2 lo = *(const LAS u32x2*)(lds + vfb + buf + dt * 128), hi = *(const LAS u32x2*)(lds + vfb + buf + dt * 128 + 4096);
;                 const u32x4 vw = (u32x4){lo.x, lo.y, hi.x, hi.y}; o[dt] = MFMA16(__builtin_bit_cast(bf16x8, vw), pf, o[dt]); }
;             SCHED_FENCE();
;             if (a < 7) NA_WRITE((8 + a + 1) % 3, (a + 1) & 1);
;             __syncthreads();
	s_waitcnt vmcnt(7)
	ds_write_b128 v249, v[36:39]
	s_waitcnt vmcnt(6)
	ds_write_b128 v249, v[48:51] offset:8192
	s_waitcnt vmcnt(5)
	ds_write_b128 v249, v[52:55] offset:16384
	s_waitcnt vmcnt(4)
	ds_write_b128 v249, v[60:63] offset:24576
	buffer_load_dwordx4 v[32:35], v208, s[92:95], s2 offen
	s_add_i32 s2, s14, 0x20e82000
	buffer_load_dwordx4 v[40:43], v208, s[92:95], s2 offen
	s_add_i32 s2, s14, 0x20e84000
	buffer_load_dwordx4 v[44:47], v208, s[92:95], s2 offen
	s_add_i32 s2, s14, 0x20e86000
	buffer_load_dwordx4 v[56:59], v208, s[92:95], s2 offen
	v_add_u32_e32 v99, 0x8000, v237
	v_add_u32_e32 v100, 0x9000, v237
	v_cvt_pk_bf16_f32 v132, v172, v173
	v_cvt_pk_bf16_f32 v133, v174, v175
	v_cvt_pk_bf16_f32 v134, v176, v177
	v_cvt_pk_bf16_f32 v135, v178, v179
	ds_read2_b64 v[164:167], v99 offset1:16
	ds_read2_b64 v[172:175], v100 offset1:16
	s_waitcnt lgkmcnt(1)
	v_mov_b32_e32 v176, v164
	s_waitcnt lgkmcnt(0)
	v_mov_b32_e32 v178, v172
	v_mov_b32_e32 v179, v173
	v_mov_b32_e32 v172, v166
	v_mov_b32_e32 v173, v167
	v_mov_b32_e32 v177, v165
	s_nop 0
	v_mfma_f32_16x16x32_bf16 v[140:143], v[172:175], v[132:135], v[140:143]
	ds_read2_b64 v[164:167], v99 offset0:32 offset1:48
	ds_read2_b64 v[172:175], v100 offset0:32 offset1:48
	v_mfma_f32_16x16x32_bf16 v[144:147], v[176:179], v[132:135], v[144:147]
	s_waitcnt lgkmcnt(1)
	v_mov_b32_e32 v176, v164
	s_waitcnt lgkmcnt(0)
	v_mov_b32_e32 v178, v172
	v_mov_b32_e32 v179, v173
	v_mov_b32_e32 v172, v166
	v_mov_b32_e32 v173, v167
	v_mov_b32_e32 v177, v165
	s_nop 0
	v_mfma_f32_16x16x32_bf16 v[148:151], v[172:175], v[132:135], v[148:151]
	ds_read2_b64 v[164:167], v99 offset0:64 offset1:80
	ds_read2_b64 v[172:175], v100 offset0:64 offset1:80
	v_mfma_f32_16x16x32_bf16 v[152:155], v[176:179], v[132:135], v[152:155]
	s_waitcnt lgkmcnt(1)
	v_mov_b32_e32 v176, v164
	s_waitcnt lgkmcnt(0)
	v_mov_b32_e32 v178, v172
	v_mov_b32_e32 v179, v173
	v_mov_b32_e32 v172, v166
	v_mov_b32_e32 v173, v167
	v_mov_b32_e32 v177, v165
	s_nop 0
	v_mfma_f32_16x16x32_bf16 v[156:159], v[172:175], v[132:135], v[156:159]
	ds_read2_b64 v[164:167], v99 offset0:96 offset1:112
	ds_read2_b64 v[172:175], v100 offset0:96 offset1:112
	v_mfma_f32_16x16x32_bf16 v[160:163], v[176:179], v[132:135], v[160:163]
	s_waitcnt lgkmcnt(1)
	v_mov_b32_e32 v176, v164
	v_mov_b32_e32 v177, v165
	s_waitcnt lgkmcnt(0)
	v_mov_b32_e32 v178, v172
	v_mov_b32_e32 v179, v173
	v_mov_b32_e32 v172, v166
	v_mov_b32_e32 v173, v167
	v_mfma_f32_16x16x32_bf16 v[168:171], v[176:179], v[132:135], v[168:171]
	s_nop 0
	v_mfma_f32_16x16x32_bf16 v[128:131], v[172:175], v[132:135], v[128:131]
	s_add_i32 s2, s14, 0x20ea0000
	s_waitcnt lgkmcnt(0)
	s_barrier
	s_waitcnt vmcnt(7)
	ds_write_b128 v249, v[64:67] offset:32768
	s_waitcnt vmcnt(6)
	ds_write_b128 v249, v[68:71] offset:40960
	s_waitcnt vmcnt(5)
	ds_write_b128 v249, v[72:75] offset:49152
	s_waitcnt vmcnt(4)
	ds_write_b128 v249, v[76:79] offset:57344
	buffer_load_dwordx4 v[36:39], v208, s[92:95], s2 offen
	s_add_i32 s2, s14, 0x20ea2000
	buffer_load_dwordx4 v[48:51], v208, s[92:95], s2 offen
	s_add_i32 s2, s14, 0x20ea4000
	buffer_load_dwordx4 v[52:55], v208, s[92:95], s2 offen
	s_add_i32 s2, s14, 0x20ea6000
	buffer_load_dwordx4 v[60:63], v208, s[92:95], s2 offen
	v_cvt_pk_bf16_f32 v132, v136, v137
	v_cvt_pk_bf16_f32 v133, v138, v180
	v_cvt_pk_bf16_f32 v134, v181, v182
	v_cvt_pk_bf16_f32 v135, v183, v184
	ds_read2_b64 v[136:139], v237 offset1:16
	ds_read2_b64 v[164:167], v98 offset1:16
	s_waitcnt lgkmcnt(1)
	v_mov_b32_e32 v172, v136
	s_waitcnt lgkmcnt(0)
	v_mov_b32_e32 v174, v164
	v_mov_b32_e32 v175, v165
	v_mov_b32_e32 v164, v138
	v_mov_b32_e32 v165, v139
	v_mov_b32_e32 v173, v137
	s_nop 0
	v_mfma_f32_16x16x32_bf16 v[136:139], v[164:167], v[132:135], v[140:143]
	s_nop 2
	ds_read2_b64 v[140:143], v237 offset0:32 offset1:48
	ds_read2_b64 v[164:167], v98 offset0:32 offset1:48
	v_mfma_f32_16x16x32_bf16 v[144:147], v[172:175], v[132:135], v[144:147]
	s_waitcnt lgkmcnt(1)
	v_mov_b32_e32 v172, v140
	s_waitcnt lgkmcnt(0)
	v_mov_b32_e32 v174, v164
	v_mov_b32_e32 v175, v165
	v_mov_b32_e32 v164, v142
	v_mov_b32_e32 v165, v143
	v_mov_b32_e32 v173, v141
	s_nop 0
	v_mfma_f32_16x16x32_bf16 v[140:143], v[164:167], v[132:135], v[148:151]
	s_nop 2
	ds_read2_b64 v[148:151], v237 offset0:64 offset1:80
	ds_read2_b64 v[164:167], v98 offset0:64 offset1:80
	v_mfma_f32_16x16x32_bf16 v[152:155], v[172:175], v[132:135], v[152:155]
	s_waitcnt lgkmcnt(1)
	v_mov_b32_e32 v172, v148
	s_waitcnt lgkmcnt(0)
	v_mov_b32_e32 v174, v164
	v_mov_b32_e32 v175, v165
	v_mov_b32_e32 v164, v150
	v_mov_b32_e32 v165, v151
	v_mov_b32_e32 v173, v149
	s_nop 0
	v_mfma_f32_16x16x32_bf16 v[148:151], v[164:167], v[132:135], v[156:159]
	s_nop 2
	ds_read2_b64 v[156:159], v237 offset0:96 offset1:112
	ds_read2_b64 v[164:167], v98 offset0:96 offset1:112
	v_mfma_f32_16x16x32_bf16 v[160:163], v[172:175], v[132:135], v[160:163]
	s_waitcnt lgkmcnt(1)
	v_mov_b32_e32 v172, v156
	v_mov_b32_e32 v173, v157
	s_waitcnt lgkmcnt(0)
	v_mov_b32_e32 v174, v164
	v_mov_b32_e32 v175, v165
	v_mov_b32_e32 v164, v158
	v_mov_b32_e32 v165, v159
	v_mfma_f32_16x16x32_bf16 v[168:171], v[172:175], v[132:135], v[168:171]
	s_nop 0
	v_mfma_f32_16x16x32_bf16 v[128:131], v[164:167], v[132:135], v[128:131]
	s_add_i32 s2, s14, 0x20ec0000
	s_waitcnt lgkmcnt(0)
	s_barrier
; __device__ __forceinline__ u32x4 pack8(const f32x4 v0, const f32x4 v1) { u32x4 w; w.x = cvt_pk_bf16(v0[0], v0[1]); w.y = cvt_pk_bf16(v0[2], v0[3]); w.z = cvt_pk_bf16(v1[0], v1[1]); w.w = cvt_pk_bf16(v1[2], v1[3]); return w; }
; #define LAS __attribute__((address_space(3)))
; #define MFMA16(a, b, c) __builtin_amdgcn_mfma_f32_16x16x32_bf16((a), (b), (c), 0, 0, 0)
; #define SCHED_FENCE() __builtin_amdgcn_sched_barrier(0)
; #define NA_ISSUE(seq_, slot_) do { _Pragma("unroll") for (int j = 0; j < 4; ++j) st[slot_][j] = bld<u32x4>(R, co, ((seq_) < 8 ? (unsigned)WS_KB + rowb + (unsigned)((seq_) * 131072) : OFF_VT + rowb + (unsigned)(((seq_) - 8) * 131072)) + (unsigned)j * 8192u); } while (0)
; #define NA_WRITE(slot_, buf_) do { _Pragma("unroll") for (int j = 0; j < 4; ++j) *(LAS u32x4*)(lds + (buf_) * NA_BUF + j * 8192 + tid * 16) = st[slot_][j]; } while (0)
; __device__ __forceinline__ void na_attn_block(LAS unsigned char* lds, rsrc_t R, int l, int bx, int G, int tid, int lane, int wave) {
;     ...
; #pragma unroll
;         for (int a = 0; a < 8; ++a) {
;             if (a + 3 < 8) NA_ISSUE(8 + a + 3, (8 + a) % 3);
;             SCHED_FENCE();
;             const int buf = (a & 1) * NA_BUF;
;             const u32x4 pw = pg8::pack8(S[a][0], S[a][1]); const bf16x8 pf = __builtin_bit_cast(bf16x8, pw);
; #pragma unroll
;             for (int dt = 0; dt < 8; ++dt) { const u32x2 lo = *(const LAS u32x2*)(lds + vfb + buf + dt * 128), hi = *(const LAS u32x2*)(lds + vfb + buf + dt * 128 + 4096);
;                 const u32x4 vw = (u32x4){lo.x, lo.y, hi.x, hi.y}; o[dt] = MFMA16(__builtin_bit_cast(bf16x8, vw), pf, o[dt]); }
;             SCHED_FENCE();
;             if (a < 7) NA_WRITE((8 + a + 1) % 3, (a + 1) & 1);
;             __syncthreads();
	s_waitcnt vmcnt(7)
	ds_write_b128 v249, v[32:35]
	s_waitcnt vmcnt(6)
	ds_write_b128 v249, v[40:43] offset:8192
	s_waitcnt vmcnt(5)
	ds_write_b128 v249, v[44:47] offset:16384
	s_waitcnt vmcnt(4)
	ds_write_b128 v249, v[56:59] offset:24576
	buffer_load_dwordx4 v[64:67], v208, s[92:95], s2 offen
	s_add_i32 s2, s14, 0x20ec2000
	buffer_load_dwordx4 v[68:71], v208, s[92:95], s2 offen
	s_add_i32 s2, s14, 0x20ec4000
	buffer_load_dwordx4 v[72:75], v208, s[92:95], s2 offen
	s_add_i32 s2, s14, 0x20ec6000
	buffer_load_dwordx4 v[76:79], v208, s[92:95], s2 offen
	v_cvt_pk_bf16_f32 v118, v120, v121
	v_cvt_pk_bf16_f32 v119, v122, v123
	v_cvt_pk_bf16_f32 v120, v124, v125
	v_cvt_pk_bf16_f32 v121, v126, v127
	ds_read2_b64 v[122:125], v99 offset1:16
	ds_read2_b64 v[132:135], v100 offset1:16
	s_waitcnt lgkmcnt(1)
	v_mov_b32_e32 v156, v122
	s_waitcnt lgkmcnt(0)
	v_mov_b32_e32 v158, v132
	v_mov_b32_e32 v159, v133
	v_mov_b32_e32 v132, v124
	v_mov_b32_e32 v133, v125
	v_mov_b32_e32 v157, v123
	s_nop 0
	v_mfma_f32_16x16x32_bf16 v[122:125], v[132:135], v[118:121], v[136:139]
	ds_read2_b64 v[132:135], v99 offset0:32 offset1:48
	s_nop 1
	ds_read2_b64 v[136:139], v100 offset0:32 offset1:48
	v_mfma_f32_16x16x32_bf16 v[144:147], v[156:159], v[118:121], v[144:147]
	s_waitcnt lgkmcnt(1)
	v_mov_b32_e32 v156, v132
	s_waitcnt lgkmcnt(0)
	v_mov_b32_e32 v158, v136
	v_mov_b32_e32 v159, v137
	v_mov_b32_e32 v136, v134
	v_mov_b32_e32 v137, v135
	v_mov_b32_e32 v157, v133
	s_nop 0
	v_mfma_f32_16x16x32_bf16 v[132:135], v[136:139], v[118:121], v[140:143]
	ds_read2_b64 v[136:139], v99 offset0:64 offset1:80
	s_nop 1
	ds_read2_b64 v[140:143], v100 offset0:64 offset1:80
	v_mfma_f32_16x16x32_bf16 v[152:155], v[156:159], v[118:121], v[152:155]
	s_waitcnt lgkmcnt(1)
	v_mov_b32_e32 v156, v136
	s_waitcnt lgkmcnt(0)
	v_mov_b32_e32 v158, v140
	v_mov_b32_e32 v159, v141
	v_mov_b32_e32 v140, v138
	v_mov_b32_e32 v141, v139
	v_mov_b32_e32 v157, v137
	s_nop 0
	v_mfma_f32_16x16x32_bf16 v[136:139], v[140:143], v[118:121], v[148:151]
	ds_read2_b64 v[140:143], v99 offset0:96 offset1:112
	s_nop 1
	ds_read2_b64 v[148:151], v100 offset0:96 offset1:112
	v_mfma_f32_16x16x32_bf16 v[156:159], v[156:159], v[118:121], v[160:163]
	s_waitcnt lgkmcnt(1)
	s_nop 1
	v_mov_b32_e32 v160, v140
	v_mov_b32_e32 v161, v141
	s_waitcnt lgkmcnt(0)
	v_mov_b32_e32 v162, v148
	v_mov_b32_e32 v163, v149
	v_mov_b32_e32 v148, v142
	v_mov_b32_e32 v149, v143
	v_mfma_f32_16x16x32_bf16 v[160:163], v[160:163], v[118:121], v[168:171]
	s_nop 0
	v_mfma_f32_16x16x32_bf16 v[118:121], v[148:151], v[118:121], v[128:131]
	s_add_i32 s2, s14, 0x20ee0000
	s_waitcnt lgkmcnt(0)
	s_barrier
	s_waitcnt vmcnt(7)
	ds_write_b128 v249, v[36:39] offset:32768
	s_waitcnt vmcnt(6)
	ds_write_b128 v249, v[48:51] offset:40960
	s_waitcnt vmcnt(5)
	ds_write_b128 v249, v[52:55] offset:49152
	s_waitcnt vmcnt(4)
	ds_write_b128 v249, v[60:63] offset:57344
	buffer_load_dwordx4 v[32:35], v208, s[92:95], s2 offen
	s_add_i32 s2, s14, 0x20ee2000
	buffer_load_dwordx4 v[40:43], v208, s[92:95], s2 offen
	s_add_i32 s2, s14, 0x20ee4000
	s_add_i32 s14, s14, 0x20ee6000
	buffer_load_dwordx4 v[44:47], v208, s[92:95], s2 offen
	buffer_load_dwordx4 v[56:59], v208, s[92:95], s14 offen
	v_cvt_pk_bf16_f32 v110, v109, v110
	v_cvt_pk_bf16_f32 v111, v111, v114
	v_cvt_pk_bf16_f32 v112, v113, v112
	v_cvt_pk_bf16_f32 v113, v115, v116
	ds_read2_b64 v[114:117], v237 offset1:16
	ds_read2_b64 v[126:129], v98 offset1:16
	s_waitcnt lgkmcnt(1)
	v_mov_b32_e32 v140, v114
	s_waitcnt lgkmcnt(0)
	v_mov_b32_e32 v142, v126
	v_mov_b32_e32 v143, v127
	v_mov_b32_e32 v126, v116
	v_mov_b32_e32 v127, v117
	v_mov_b32_e32 v141, v115
	s_nop 0
	v_mfma_f32_16x16x32_bf16 v[114:117], v[126:129], v[110:113], v[122:125]
	s_nop 2
	ds_read2_b64 v[122:125], v237 offset0:32 offset1:48
	ds_read2_b64 v[126:129], v98 offset0:32 offset1:48
	v_mfma_f32_16x16x32_bf16 v[140:143], v[140:143], v[110:113], v[144:147]
	s_waitcnt lgkmcnt(0)
	s_nop 1
	v_mov_b32_e32 v146, v126
	v_mov_b32_e32 v147, v127
	v_mov_b32_e32 v126, v124
	v_mov_b32_e32 v127, v125
	v_mov_b32_e32 v144, v122
	v_mov_b32_e32 v145, v123
	v_mfma_f32_16x16x32_bf16 v[122:125], v[126:129], v[110:113], v[132:135]
	ds_read2_b64 v[126:129], v237 offset0:64 offset1:80
	s_nop 1
	ds_read2_b64 v[130:133], v98 offset0:64 offset1:80
	s_waitcnt lgkmcnt(1)
	v_mov_b32_e32 v148, v126
	s_waitcnt lgkmcnt(0)
	v_mov_b32_e32 v150, v130
	v_mov_b32_e32 v151, v131
	v_mov_b32_e32 v130, v128
	v_mov_b32_e32 v131, v129
	v_mov_b32_e32 v149, v127
	v_mfma_f32_16x16x32_bf16 v[144:147], v[144:147], v[110:113], v[152:155]
	v_mfma_f32_16x16x32_bf16 v[126:129], v[130:133], v[110:113], v[136:139]
	ds_read2_b64 v[130:133], v237 offset0:96 offset1:112
	s_nop 1
	ds_read2_b64 v[134:137], v98 offset0:96 offset1:112
	s_waitcnt lgkmcnt(1)
	v_mov_b32_e32 v152, v130
	v_mov_b32_e32 v153, v131
	s_waitcnt lgkmcnt(0)
	v_mov_b32_e32 v154, v134
	v_mov_b32_e32 v155, v135
	v_mov_b32_e32 v134, v132
	v_mov_b32_e32 v135, v133
	v_mfma_f32_16x16x32_bf16 v[148:151], v[148:151], v[110:113], v[156:159]
	v_mfma_f32_16x16x32_bf16 v[152:155], v[152:155], v[110:113], v[160:163]
	v_mfma_f32_16x16x32_bf16 v[110:113], v[134:137], v[110:113], v[118:121]
	s_waitcnt lgkmcnt(0)
	s_barrier
; __device__ __forceinline__ u32x4 pack8(const f32x4 v0, const f32x4 v1) { u32x4 w; w.x = cvt_pk_bf16(v0[0], v0[1]); w.y = cvt_pk_bf16(v0[2], v0[3]); w.z = cvt_pk_bf16(v1[0], v1[1]); w.w = cvt_pk_bf16(v1[2], v1[3]); return w; }
; #define LAS __attribute__((address_space(3)))
; #define MFMA16(a, b, c) __builtin_amdgcn_mfma_f32_16x16x32_bf16((a), (b), (c), 0, 0, 0)
; #define SCHED_FENCE() __builtin_amdgcn_sched_barrier(0)
; #define NA_ISSUE(seq_, slot_) do { _Pragma("unroll") for (int j = 0; j < 4; ++j) st[slot_][j] = bld<u32x4>(R, co, ((seq_) < 8 ? (unsigned)WS_KB + rowb + (unsigned)((seq_) * 131072) : OFF_VT + rowb + (unsigned)(((seq_) - 8) * 131072)) + (unsigned)j * 8192u); } while (0)
; #define NA_WRITE(slot_, buf_) do { _Pragma("unroll") for (int j = 0; j < 4; ++j) *(LAS u32x4*)(lds + (buf_) * NA_BUF + j * 8192 + tid * 16) = st[slot_][j]; } while (0)
; __device__ __forceinline__ void na_attn_block(LAS unsigned char* lds, rsrc_t R, int l, int bx, int G, int tid, int lane, int wave) {
;     ...
; #pragma unroll
;         for (int a = 0; a < 8; ++a) {
;             if (a + 3 < 8) NA_ISSUE(8 + a + 3, (8 + a) % 3);
;             SCHED_FENCE();
;             const int buf = (a & 1) * NA_BUF;
;             const u32x4 pw = pg8::pack8(S[a][0], S[a][1]); const bf16x8 pf = __builtin_bit_cast(bf16x8, pw);
; #pragma unroll
;             for (int dt = 0; dt < 8; ++dt) { const u32x2 lo = *(const LAS u32x2*)(lds + vfb + buf + dt * 128), hi = *(const LAS u32x2*)(lds + vfb + buf + dt * 128 + 4096);
;                 const u32x4 vw = (u32x4){lo.x, lo.y, hi.x, hi.y}; o[dt] = MFMA16(__builtin_bit_cast(bf16x8, vw), pf, o[dt]); }
;             SCHED_FENCE();
;             if (a < 7) NA_WRITE((8 + a + 1) % 3, (a + 1) & 1);
;             __syncthreads();
;         }
;     ...
;         const float inv = __builtin_amdgcn_rcpf(sum); float ss = 0.f;
	s_waitcnt vmcnt(7)
	ds_write_b128 v249, v[64:67]
	s_waitcnt vmcnt(6)
	ds_write_b128 v249, v[68:71] offset:8192
	s_waitcnt vmcnt(5)
	ds_write_b128 v249, v[72:75] offset:16384
	s_waitcnt vmcnt(4)
	ds_write_b128 v249, v[76:79] offset:24576
	v_cvt_pk_bf16_f32 v36, v101, v102
	v_cvt_pk_bf16_f32 v37, v103, v104
	v_cvt_pk_bf16_f32 v38, v105, v106
	v_cvt_pk_bf16_f32 v39, v107, v108
	ds_read2_b64 v[48:51], v99 offset1:16
	ds_read2_b64 v[52:55], v100 offset1:16
	s_waitcnt lgkmcnt(1)
	v_mov_b32_e32 v60, v48
	s_waitcnt lgkmcnt(0)
	v_mov_b32_e32 v62, v52
	v_mov_b32_e32 v63, v53
	v_mov_b32_e32 v52, v50
	v_mov_b32_e32 v53, v51
	v_mov_b32_e32 v61, v49
	s_nop 0
	v_mfma_f32_16x16x32_bf16 v[48:51], v[52:55], v[36:39], v[114:117]
	ds_read2_b64 v[52:55], v99 offset0:32 offset1:48
	ds_read2_b64 v[102:105], v100 offset0:32 offset1:48
	s_waitcnt lgkmcnt(1)
	v_mov_b32_e32 v106, v52
	s_waitcnt lgkmcnt(0)
	v_mov_b32_e32 v108, v102
	v_mov_b32_e32 v109, v103
	v_mov_b32_e32 v102, v54
	v_mov_b32_e32 v103, v55
	v_mov_b32_e32 v107, v53
	v_mfma_f32_16x16x32_bf16 v[60:63], v[60:63], v[36:39], v[140:143]
	v_mfma_f32_16x16x32_bf16 v[52:55], v[102:105], v[36:39], v[122:125]
	ds_read2_b64 v[102:105], v99 offset0:64 offset1:80
	ds_read2_b64 v[114:117], v100 offset0:64 offset1:80
	s_waitcnt lgkmcnt(1)
	v_mov_b32_e32 v118, v102
	s_waitcnt lgkmcnt(0)
	v_mov_b32_e32 v120, v114
	v_mov_b32_e32 v121, v115
	v_mov_b32_e32 v114, v104
	v_mov_b32_e32 v115, v105
	v_mov_b32_e32 v119, v103
	v_mfma_f32_16x16x32_bf16 v[106:109], v[106:109], v[36:39], v[144:147]
	v_mfma_f32_16x16x32_bf16 v[102:105], v[114:117], v[36:39], v[126:129]
	ds_read2_b64 v[114:117], v99 offset0:96 offset1:112
	ds_read2_b64 v[122:125], v100 offset0:96 offset1:112
	s_waitcnt lgkmcnt(1)
	v_mov_b32_e32 v126, v114
	v_mov_b32_e32 v127, v115
	s_waitcnt lgkmcnt(0)
	v_mov_b32_e32 v128, v122
	v_mov_b32_e32 v129, v123
	v_mov_b32_e32 v122, v116
	v_mov_b32_e32 v123, v117
	v_mfma_f32_16x16x32_bf16 v[118:121], v[118:121], v[36:39], v[148:151]
	v_mfma_f32_16x16x32_bf16 v[126:129], v[126:129], v[36:39], v[152:155]
	v_mfma_f32_16x16x32_bf16 v[36:39], v[122:125], v[36:39], v[110:113]
	s_waitcnt lgkmcnt(0)
	s_barrier
	s_waitcnt vmcnt(3)
	ds_write_b128 v249, v[32:35] offset:32768
	s_waitcnt vmcnt(2)
	ds_write_b128 v249, v[40:43] offset:40960
	s_waitcnt vmcnt(1)
	ds_write_b128 v249, v[44:47] offset:49152
	s_waitcnt vmcnt(0)
	ds_write_b128 v249, v[56:59] offset:57344
	v_cvt_pk_bf16_f32 v64, v90, v91
	v_cvt_pk_bf16_f32 v65, v92, v93
	v_cvt_pk_bf16_f32 v66, v94, v95
	v_cvt_pk_bf16_f32 v67, v96, v97
	ds_read2_b64 v[68:71], v237 offset1:16
	ds_read2_b64 v[72:75], v98 offset1:16
	s_waitcnt lgkmcnt(1)
	v_mov_b32_e32 v76, v68
	s_waitcnt lgkmcnt(0)
	v_mov_b32_e32 v78, v72
	v_mov_b32_e32 v79, v73
	v_mov_b32_e32 v72, v70
	v_mov_b32_e32 v73, v71
	v_mov_b32_e32 v77, v69
	s_nop 0
	v_mfma_f32_16x16x32_bf16 v[48:51], v[72:75], v[64:67], v[48:51]
	ds_read2_b64 v[68:71], v237 offset0:32 offset1:48
	ds_read2_b64 v[72:75], v98 offset0:32 offset1:48
	v_mfma_f32_16x16x32_bf16 v[60:63], v[76:79], v[64:67], v[60:63]
	s_waitcnt lgkmcnt(1)
	v_mov_b32_e32 v76, v68
	s_waitcnt lgkmcnt(0)
	v_mov_b32_e32 v78, v72
	v_mov_b32_e32 v79, v73
	v_mov_b32_e32 v72, v70
	v_mov_b32_e32 v73, v71
	v_mov_b32_e32 v77, v69
	s_nop 0
	v_mfma_f32_16x16x32_bf16 v[52:55], v[72:75], v[64:67], v[52:55]
	ds_read2_b64 v[68:71], v237 offset0:64 offset1:80
	ds_read2_b64 v[72:75], v98 offset0:64 offset1:80
	s_waitcnt lgkmcnt(1)
	v_mov_b32_e32 v90, v68
	s_waitcnt lgkmcnt(0)
	v_mov_b32_e32 v92, v72
	v_mov_b32_e32 v93, v73
	v_mov_b32_e32 v72, v70
	v_mov_b32_e32 v73, v71
	v_mov_b32_e32 v91, v69
	v_mfma_f32_16x16x32_bf16 v[76:79], v[76:79], v[64:67], v[106:109]
	v_mfma_f32_16x16x32_bf16 v[68:71], v[72:75], v[64:67], v[102:105]
	ds_read2_b64 v[72:75], v237 offset0:96 offset1:112
	ds_read2_b64 v[94:97], v98 offset0:96 offset1:112
	s_waitcnt lgkmcnt(1)
	v_mov_b32_e32 v102, v72
	v_mov_b32_e32 v103, v73
	s_waitcnt lgkmcnt(0)
	v_mov_b32_e32 v104, v94
	v_mov_b32_e32 v105, v95
	v_mov_b32_e32 v94, v74
	v_mov_b32_e32 v95, v75
	v_mfma_f32_16x16x32_bf16 v[90:93], v[90:93], v[64:67], v[118:121]
	v_mfma_f32_16x16x32_bf16 v[102:105], v[102:105], v[64:67], v[126:129]
	v_mfma_f32_16x16x32_bf16 v[36:39], v[94:97], v[64:67], v[36:39]
	s_waitcnt lgkmcnt(0)
	s_barrier
	v_cvt_pk_bf16_f32 v32, v82, v83
	v_cvt_pk_bf16_f32 v33, v84, v85
	v_cvt_pk_bf16_f32 v34, v86, v87
	v_cvt_pk_bf16_f32 v35, v88, v89
	ds_read2_b64 v[40:43], v99 offset1:16
	ds_read2_b64 v[44:47], v100 offset1:16
	s_waitcnt lgkmcnt(1)
	v_mov_b32_e32 v56, v40
	s_waitcnt lgkmcnt(0)
	v_mov_b32_e32 v58, v44
	v_mov_b32_e32 v59, v45
	v_mov_b32_e32 v44, v42
	v_mov_b32_e32 v45, v43
	v_mov_b32_e32 v57, v41
	s_nop 0
	v_mfma_f32_16x16x32_bf16 v[40:43], v[44:47], v[32:35], v[48:51]
	ds_read2_b64 v[44:47], v99 offset0:32 offset1:48
	s_nop 1
	ds_read2_b64 v[48:51], v100 offset0:32 offset1:48
	v_mfma_f32_16x16x32_bf16 v[56:59], v[56:59], v[32:35], v[60:63]
	s_waitcnt lgkmcnt(0)
	s_nop 1
	v_mov_b32_e32 v62, v48
	v_mov_b32_e32 v63, v49
	v_mov_b32_e32 v48, v46
	v_mov_b32_e32 v49, v47
	v_mov_b32_e32 v60, v44
	v_mov_b32_e32 v61, v45
	v_mfma_f32_16x16x32_bf16 v[44:47], v[48:51], v[32:35], v[52:55]
	ds_read2_b64 v[48:51], v99 offset0:64 offset1:80
	s_nop 1
	ds_read2_b64 v[52:55], v100 offset0:64 offset1:80
	s_waitcnt lgkmcnt(1)
	v_mov_b32_e32 v64, v48
	s_waitcnt lgkmcnt(0)
	v_mov_b32_e32 v66, v52
	v_mov_b32_e32 v67, v53
	v_mov_b32_e32 v52, v50
	v_mov_b32_e32 v53, v51
	v_mov_b32_e32 v65, v49
	v_mfma_f32_16x16x32_bf16 v[60:63], v[60:63], v[32:35], v[76:79]
	v_mfma_f32_16x16x32_bf16 v[48:51], v[52:55], v[32:35], v[68:71]
	ds_read2_b64 v[52:55], v99 offset0:96 offset1:112
	s_nop 1
	ds_read2_b64 v[68:71], v100 offset0:96 offset1:112
	s_waitcnt lgkmcnt(1)
	v_mov_b32_e32 v72, v52
	v_mov_b32_e32 v73, v53
	s_waitcnt lgkmcnt(0)
	v_mov_b32_e32 v74, v68
	v_mov_b32_e32 v75, v69
	v_mov_b32_e32 v68, v54
	v_mov_b32_e32 v69, v55
	v_mfma_f32_16x16x32_bf16 v[64:67], v[64:67], v[32:35], v[90:93]
	v_mfma_f32_16x16x32_bf16 v[72:75], v[72:75], v[32:35], v[102:105]
	v_mfma_f32_16x16x32_bf16 v[32:35], v[68:71], v[32:35], v[36:39]
	s_nop 2
	v_add_f32_e32 v36, v80, v81
	v_rcp_f32_e32 v36, v36
	s_lshl_b32 s2, s12, 12
	s_barrier
; __device__ __forceinline__ unsigned cvt_pk_bf16(float lo, float hi) { unsigned r; asm volatile("v_cvt_pk_bf16_f32 %0, %1, %2" : "=v"(r) : "v"(lo), "v"(hi)); return r; }
; __device__ __forceinline__ float sq4(const f32x4 v) { return (v[0] * v[0] + v[1] * v[1]) + (v[2] * v[2] + v[3] * v[3]); }
; __device__ __forceinline__ float sum_fq(float v) { v += __shfl_xor(v, 16); v += __shfl_xor(v, 32); return v; }
; __device__ __forceinline__ void na_attn_block(LAS unsigned char* lds, rsrc_t R, int l, int bx, int G, int tid, int lane, int wave) {
;     ...
;         const float inv = __builtin_amdgcn_rcpf(sum); float ss = 0.f;
; #pragma unroll
;         for (int dt = 0; dt < 8; ++dt) { o[dt] = o[dt] * inv; ss += pg8::sq4(o[dt]); }
;         ss = pg8::sum_fq(ss);
;         const float rn = __builtin_amdgcn_rsqf(ss * (1.f / HD) + EPS);
;         const unsigned y_off = OFF_Y + (unsigned)((b * SEQ + r * 64 + 16 * qg) * DM + h * HD) * 2u;
; #pragma unroll
;         for (int dt = 0; dt < 8; ++dt) { u32x2 w; w.x = pg8::cvt_pk_bf16(o[dt][0] * rn, o[dt][1] * rn); w.y = pg8::cvt_pk_bf16(o[dt][2] * rn, o[dt][3] * rn); bst<u32x2>(R, yo, y_off + 32 * dt, w); }
	v_pk_mul_f32 v[52:53], v[36:37], v[56:57] op_sel_hi:[0,1]
	v_pk_mul_f32 v[40:41], v[36:37], v[40:41] op_sel_hi:[0,1]
	v_pk_mul_f32 v[38:39], v[36:37], v[58:59] op_sel_hi:[0,1]
	v_pk_mul_f32 v[42:43], v[36:37], v[42:43] op_sel_hi:[0,1]
	v_mov_b32_e32 v56, v53
	v_mov_b32_e32 v57, v41
	v_mov_b32_e32 v54, v52
	v_mov_b32_e32 v55, v40
	v_pk_mul_f32 v[56:57], v[56:57], v[56:57]
	v_mov_b32_e32 v58, v39
	v_mov_b32_e32 v59, v43
	v_pk_fma_f32 v[54:55], v[54:55], v[54:55], v[56:57]
	v_mov_b32_e32 v56, v38
	v_mov_b32_e32 v57, v42
	v_pk_mul_f32 v[58:59], v[58:59], v[58:59]
	v_pk_mul_f32 v[64:65], v[36:37], v[64:65] op_sel_hi:[0,1]
	v_pk_fma_f32 v[56:57], v[56:57], v[56:57], v[58:59]
	v_pk_mul_f32 v[58:59], v[36:37], v[60:61] op_sel_hi:[0,1]
	v_pk_add_f32 v[54:55], v[54:55], v[56:57]
	v_pk_mul_f32 v[56:57], v[36:37], v[62:63] op_sel_hi:[0,1]
	v_pk_mul_f32 v[60:61], v[56:57], v[56:57]
	v_pk_mul_f32 v[62:63], v[58:59], v[58:59]
	v_pk_mul_f32 v[46:47], v[36:37], v[46:47] op_sel_hi:[0,1]
	v_pk_mov_b32 v[68:69], v[62:63], v[60:61] op_sel:[1,0]
	v_mov_b32_e32 v63, v61
	v_pk_add_f32 v[60:61], v[68:69], v[62:63]
	v_pk_mul_f32 v[44:45], v[36:37], v[44:45] op_sel_hi:[0,1]
	v_pk_mul_f32 v[62:63], v[36:37], v[66:67] op_sel_hi:[0,1]
	v_mul_f32_e32 v37, v64, v64
	v_mul_f32_e32 v66, v65, v65
	v_pk_add_f32 v[54:55], v[54:55], v[54:55] op_sel:[0,1] op_sel_hi:[1,0]
	v_pk_add_f32 v[60:61], v[60:61], v[60:61] op_sel:[0,1] op_sel_hi:[1,0]
	v_mov_b32_e32 v55, v37
	v_mov_b32_e32 v61, v66
	v_pk_add_f32 v[54:55], v[54:55], v[60:61]
	v_mul_f32_e32 v60, v45, v45
	v_mul_f32_e32 v67, v62, v62
	v_pk_fma_f32 v[60:61], v[44:45], v[44:45], v[60:61] op_sel_hi:[1,1,0]
	v_mul_f32_e32 v66, v47, v47
	v_mul_f32_e32 v68, v63, v63
	v_mov_b32_e32 v61, v67
	v_pk_fma_f32 v[66:67], v[46:47], v[46:47], v[66:67] op_sel_hi:[1,1,0]
	v_pk_mul_f32 v[50:51], v[36:37], v[50:51] op_sel_hi:[0,1]
	v_mov_b32_e32 v67, v68
	v_pk_add_f32 v[60:61], v[60:61], v[66:67]
	v_pk_mul_f32 v[48:49], v[36:37], v[48:49] op_sel_hi:[0,1]
	v_pk_add_f32 v[54:55], v[54:55], v[60:61]
	v_pk_mul_f32 v[60:61], v[50:51], v[50:51]
	v_pk_mul_f32 v[66:67], v[48:49], v[48:49]
	v_pk_mul_f32 v[32:33], v[36:37], v[32:33] op_sel_hi:[0,1]
	v_pk_mov_b32 v[68:69], v[66:67], v[60:61] op_sel:[1,0]
	v_mov_b32_e32 v67, v61
	v_pk_add_f32 v[60:61], v[68:69], v[66:67]
	v_pk_mul_f32 v[66:67], v[36:37], v[74:75] op_sel_hi:[0,1]
	v_pk_mul_f32 v[68:69], v[36:37], v[72:73] op_sel_hi:[0,1]
	v_pk_mul_f32 v[34:35], v[36:37], v[34:35] op_sel_hi:[0,1]
	v_mul_f32_e32 v70, v32, v32
	v_mul_f32_e32 v71, v33, v33
	v_pk_add_f32 v[36:37], v[54:55], v[54:55] op_sel:[0,1] op_sel_hi:[1,0]
	v_pk_add_f32 v[54:55], v[60:61], v[60:61] op_sel:[0,1] op_sel_hi:[1,0]
	v_mov_b32_e32 v37, v70
	v_mov_b32_e32 v55, v71
	v_pk_add_f32 v[36:37], v[36:37], v[54:55]
	v_mul_f32_e32 v54, v69, v69
	v_mul_f32_e32 v60, v67, v67
	v_mul_f32_e32 v72, v34, v34
	v_mul_f32_e32 v73, v35, v35
	v_pk_fma_f32 v[54:55], v[68:69], v[68:69], v[54:55] op_sel_hi:[1,1,0]
	v_pk_fma_f32 v[60:61], v[66:67], v[66:67], v[60:61] op_sel_hi:[1,1,0]
	v_mov_b32_e32 v55, v72
	v_mov_b32_e32 v61, v73
	v_pk_add_f32 v[54:55], v[54:55], v[60:61]
	s_nop 0
	v_pk_add_f32 v[36:37], v[36:37], v[54:55]
	s_add_i32 s2, s13, s2
	v_add_f32_e32 v36, v36, v37
	ds_bpermute_b32 v37, v235, v36
	s_add_i32 s2, s2, 0x24e00000
	s_or_b32 s3, s2, 32
	s_add_i32 s11, s11, s86
	s_add_i32 s10, s10, s5
	s_waitcnt lgkmcnt(0)
	v_add_f32_e32 v36, v36, v37
	ds_bpermute_b32 v37, v236, v36
	s_waitcnt lgkmcnt(0)
	v_add_f32_e32 v36, v36, v37
	v_fmamk_f32 v36, v36, 0x3c000000, v218
	v_rsq_f32_e32 v54, v36
	s_nop 0
	v_mul_f32_e32 v36, v52, v54
	v_mul_f32_e32 v37, v53, v54
	v_cvt_pk_bf16_f32 v36, v36, v37
	v_mul_f32_e32 v37, v38, v54
	v_mul_f32_e32 v38, v39, v54
	v_cvt_pk_bf16_f32 v37, v37, v38
	buffer_store_dwordx2 v[36:37], v233, s[92:95], s2 offen
	v_mul_f32_e32 v36, v40, v54
	v_mul_f32_e32 v37, v41, v54
	v_cvt_pk_bf16_f32 v36, v36, v37
	v_mul_f32_e32 v37, v42, v54
	v_mul_f32_e32 v38, v43, v54
	v_cvt_pk_bf16_f32 v37, v37, v38
	buffer_store_dwordx2 v[36:37], v233, s[92:95], s3 offen
	v_mul_f32_e32 v36, v58, v54
	v_mul_f32_e32 v37, v59, v54
	v_cvt_pk_bf16_f32 v36, v36, v37
	v_mul_f32_e32 v37, v56, v54
	v_mul_f32_e32 v38, v57, v54
	v_cvt_pk_bf16_f32 v37, v37, v38
	s_or_b32 s3, s2, 64
	buffer_store_dwordx2 v[36:37], v233, s[92:95], s3 offen
	v_mul_f32_e32 v36, v44, v54
	v_mul_f32_e32 v37, v45, v54
	v_cvt_pk_bf16_f32 v36, v36, v37
	v_mul_f32_e32 v37, v46, v54
	v_mul_f32_e32 v38, v47, v54
	v_cvt_pk_bf16_f32 v37, v37, v38
	s_or_b32 s3, s2, 0x60
	buffer_store_dwordx2 v[36:37], v233, s[92:95], s3 offen
	v_mul_f32_e32 v36, v64, v54
	v_mul_f32_e32 v37, v65, v54
	v_cvt_pk_bf16_f32 v36, v36, v37
	v_mul_f32_e32 v37, v62, v54
	v_mul_f32_e32 v38, v63, v54
	v_cvt_pk_bf16_f32 v37, v37, v38
	s_or_b32 s3, s2, 0x80
	buffer_store_dwordx2 v[36:37], v233, s[92:95], s3 offen
	v_mul_f32_e32 v36, v48, v54
	v_mul_f32_e32 v37, v49, v54
	v_cvt_pk_bf16_f32 v36, v36, v37
	v_mul_f32_e32 v37, v50, v54
	v_mul_f32_e32 v38, v51, v54
	v_cvt_pk_bf16_f32 v37, v37, v38
	s_or_b32 s3, s2, 0xa0
	buffer_store_dwordx2 v[36:37], v233, s[92:95], s3 offen
	v_mul_f32_e32 v36, v68, v54
	v_mul_f32_e32 v37, v69, v54
	v_cvt_pk_bf16_f32 v36, v36, v37
	v_mul_f32_e32 v37, v66, v54
	s_or_b32 s3, s2, 0xc0
	v_mul_f32_e32 v32, v32, v54
	v_mul_f32_e32 v33, v33, v54
	s_or_b32 s2, s2, 0xe0
	v_mul_f32_e32 v38, v67, v54
	v_cvt_pk_bf16_f32 v37, v37, v38
	buffer_store_dwordx2 v[36:37], v233, s[92:95], s3 offen
	v_cvt_pk_bf16_f32 v32, v32, v33
	v_mul_f32_e32 v33, v34, v54
	s_cmpk_gt_i32 s11, 0x7ff
	v_mul_f32_e32 v34, v35, v54
	v_cvt_pk_bf16_f32 v33, v33, v34
	buffer_store_dwordx2 v[32:33], v233, s[92:95], s2 offen
	s_cbranch_scc1 .LBB0_313
; __device__ __forceinline__ float sum_fq(float v) { v += __shfl_xor(v, 16); v += __shfl_xor(v, 32); return v; }
; #define LAS __attribute__((address_space(3)))
; #define SCHED_FENCE() __builtin_amdgcn_sched_barrier(0)
; #define NA_ISSUE(seq_, slot_) do { _Pragma("unroll") for (int j = 0; j < 4; ++j) st[slot_][j] = bld<u32x4>(R, co, ((seq_) < 8 ? (unsigned)WS_KB + rowb + (unsigned)((seq_) * 131072) : OFF_VT + rowb + (unsigned)(((seq_) - 8) * 131072)) + (unsigned)j * 8192u); } while (0)
; __device__ __forceinline__ void na_attn_block(LAS unsigned char* lds, rsrc_t R, int l, int bx, int G, int tid, int lane, int wave) {
;     ...
;         const int hp = u & 3, r = (u >> 2) & 127, b = u >> 9, h = 2 * hp + hsel;
;         int start = r - 4; start = start < 0 ? 0 : (start > 120 ? 120 : start);
;         const unsigned rowb = (unsigned)(((b * 128 + start) * 8 + 2 * hp) * 16384);
;         u32x4 st[3][4];
;     ...
;         u32x4 qraw[4]; float s0, s1;
;         { const unsigned q_off = OFF_PROJ + (unsigned)((b * SEQ + r * 64 + 16 * qg) * PROJ_W + h * HD) * 2u;
; #pragma unroll
;           for (int ks = 0; ks < 4; ++ks) qraw[ks] = bld<u32x4>(R, qo, q_off + 64 * ks);
;           const int hs = wave & 1, a0 = wave >> 1;
;           const unsigned sso = OFF_SS + (unsigned)(SS_H + (size_t)(l * 20 + 2 * hp + hs) * NTOK + b * SEQ + (start + a0) * 64) * 4u;
;           s0 = bld<float>(R, (unsigned)(lane * 4), sso); s1 = bld<float>(R, (unsigned)(lane * 4), sso + 4u * 64u * 4u); }
;         SCHED_FENCE();
;         NA_ISSUE(0, 0); NA_ISSUE(1, 1); NA_ISSUE(2, 2);
;         SCHED_FENCE();
;         *(LAS float*)(lds + NA_SSK + tid * 4) = __builtin_amdgcn_rsqf(s0 * (1.f / HD) + EPS); *(LAS float*)(lds + NA_SSK + (tid + 512) * 4) = __builtin_amdgcn_rsqf(s1 * (1.f / HD) + EPS);
;         bf16x8 qf[4];
;         { float qv[4][8]; float ss = 0.f;
; #pragma unroll
;           for (int ks = 0; ks < 4; ++ks)
; #pragma unroll
;               for (int j = 0; j < 4; ++j) { const unsigned w = qraw[ks][j]; qv[ks][2 * j] = __builtin_bit_cast(float, w << 16); qv[ks][2 * j + 1] = __builtin_bit_cast(float, w & 0xffff0000u); ss += qv[ks][2 * j] * qv[ks][2 * j] + qv[ks][2 * j + 1] * qv[ks][2 * j + 1]; }
;           ss = pg8::sum_fq(ss);
;           const float rq = __builtin_amdgcn_rsqf(ss * (1.f / HD) + EPS);
.Lna2_185:
	s_bfe_u32 s2, s11, 0x70002
	v_med3_u32 v250, s2, 4, v222
	s_ashr_i32 s16, s11, 9
	v_readfirstlane_b32 s15, v250
	s_add_i32 s15, s15, -4
	s_lshl_b32 s12, s16, 10
	s_lshl_b32 s13, s15, 3
	s_and_b32 s17, s10, 6
	s_add_i32 s13, s13, s12
	s_or_b32 s14, s13, s17
	s_lshl_b32 s12, s16, 13
	s_lshl_b32 s13, s2, 6
	v_readlane_b32 s3, v253, 32
	s_or_b32 s12, s13, s12
	v_readlane_b32 s13, v253, 30
	s_add_i32 s3, s17, s3
	s_or_b32 s12, s12, s13
	s_lshl_b32 s13, s3, 8
	s_mul_i32 s18, s12, 0x1800
	s_add_i32 s18, s13, s18
	s_add_i32 s18, s18, 0x14e00000
	s_or_b32 s19, s18, 64
	buffer_load_dwordx4 v[64:67], v232, s[40:43], s18 offen
	buffer_load_dwordx4 v[68:71], v232, s[40:43], s19 offen
	s_or_b32 s19, s18, 0x80
	s_or_b32 s18, s18, 0xc0
	buffer_load_dwordx4 v[84:87], v232, s[40:43], s19 offen
	buffer_load_dwordx4 v[92:95], v232, s[40:43], s18 offen
	s_add_i32 s17, s4, s17
	v_readlane_b32 s18, v253, 37
	s_add_i32 s18, s15, s18
	s_lshl_b32 s17, s17, 17
	s_lshl_b32 s16, s16, 15
	s_lshl_b32 s18, s18, 8
	s_add_i32 s16, s16, s17
	s_add_i32 s16, s16, s18
	s_add_i32 s17, s16, 0x1a0000
	s_add_i32 s16, s16, 0x1a0400
	buffer_load_dword v96, v234, s[40:43], s17 offen
	buffer_load_dword v97, v234, s[40:43], s16 offen
	s_lshl_b32 s14, s14, 14
	s_add_i32 s16, s14, 0x30e00000
	buffer_load_dwordx4 v[72:75], v208, s[40:43], s16 offen
	s_add_i32 s16, s14, 0x30e02000
	buffer_load_dwordx4 v[76:79], v208, s[40:43], s16 offen
	s_add_i32 s16, s14, 0x30e04000
	buffer_load_dwordx4 v[80:83], v208, s[40:43], s16 offen
	s_add_i32 s16, s14, 0x30e06000
	buffer_load_dwordx4 v[88:91], v208, s[40:43], s16 offen
	s_add_i32 s16, s14, 0x30e20000
	buffer_load_dwordx4 v[48:51], v208, s[40:43], s16 offen
	s_add_i32 s16, s14, 0x30e22000
	buffer_load_dwordx4 v[52:55], v208, s[40:43], s16 offen
	s_add_i32 s16, s14, 0x30e24000
	buffer_load_dwordx4 v[56:59], v208, s[40:43], s16 offen
	s_add_i32 s16, s14, 0x30e26000
	buffer_load_dwordx4 v[60:63], v208, s[40:43], s16 offen
	s_add_i32 s16, s14, 0x30e40000
	buffer_load_dwordx4 v[32:35], v208, s[40:43], s16 offen
	s_add_i32 s16, s14, 0x30e42000
	buffer_load_dwordx4 v[36:39], v208, s[40:43], s16 offen
	s_add_i32 s16, s14, 0x30e44000
	buffer_load_dwordx4 v[40:43], v208, s[40:43], s16 offen
	s_add_i32 s16, s14, 0x30e46000
	buffer_load_dwordx4 v[44:47], v208, s[40:43], s16 offen
	s_waitcnt vmcnt(0)
	v_and_b32_e32 v101, 0xffff0000, v64
	v_and_b32_e32 v103, 0xffff0000, v65
	v_lshlrev_b32_e32 v100, 16, v64
	v_mul_f32_e32 v64, v101, v101
	v_lshlrev_b32_e32 v102, 16, v65
	v_mul_f32_e32 v65, v103, v103
	v_fmac_f32_e32 v64, v100, v100
	v_fmac_f32_e32 v65, v102, v102
	v_lshlrev_b32_e32 v104, 16, v66
	v_and_b32_e32 v66, 0xffff0000, v66
	v_add_f32_e32 v64, v64, v65
	v_mul_f32_e32 v65, v66, v66
	v_fmac_f32_e32 v65, v104, v104
	v_lshlrev_b32_e32 v105, 16, v67
	v_and_b32_e32 v67, 0xffff0000, v67
	v_add_f32_e32 v64, v65, v64
	v_mul_f32_e32 v65, v67, v67
	v_fmac_f32_e32 v65, v105, v105
	v_lshlrev_b32_e32 v106, 16, v68
	v_and_b32_e32 v68, 0xffff0000, v68
	v_add_f32_e32 v64, v65, v64
	v_mul_f32_e32 v65, v68, v68
	v_fmac_f32_e32 v65, v106, v106
	v_lshlrev_b32_e32 v107, 16, v69
	v_and_b32_e32 v69, 0xffff0000, v69
	v_add_f32_e32 v64, v65, v64
	v_mul_f32_e32 v65, v69, v69
	v_fmac_f32_e32 v65, v107, v107
	v_lshlrev_b32_e32 v108, 16, v70
	v_and_b32_e32 v70, 0xffff0000, v70
	v_add_f32_e32 v64, v65, v64
	v_mul_f32_e32 v65, v70, v70
	v_fmac_f32_e32 v65, v108, v108
	v_lshlrev_b32_e32 v109, 16, v71
	v_and_b32_e32 v71, 0xffff0000, v71
	v_add_f32_e32 v64, v65, v64
	v_mul_f32_e32 v65, v71, v71
	v_fmac_f32_e32 v65, v109, v109
	v_and_b32_e32 v111, 0xffff0000, v84
	v_add_f32_e32 v64, v65, v64
	v_lshlrev_b32_e32 v110, 16, v84
	v_mul_f32_e32 v65, v111, v111
	v_fmac_f32_e32 v65, v110, v110
	v_and_b32_e32 v113, 0xffff0000, v85
	v_fmamk_f32 v96, v96, 0x3c000000, v218
	v_fmamk_f32 v97, v97, 0x3c000000, v218
	v_add_f32_e32 v64, v65, v64
	v_lshlrev_b32_e32 v112, 16, v85
	v_mul_f32_e32 v65, v113, v113
	v_rsq_f32_e32 v96, v96
	v_rsq_f32_e32 v97, v97
	v_fmac_f32_e32 v65, v112, v112
	v_and_b32_e32 v115, 0xffff0000, v86
	v_add_f32_e32 v64, v65, v64
	v_lshlrev_b32_e32 v114, 16, v86
	v_mul_f32_e32 v65, v115, v115
	v_fmac_f32_e32 v65, v114, v114
	v_and_b32_e32 v117, 0xffff0000, v87
	v_add_f32_e32 v64, v65, v64
	v_lshlrev_b32_e32 v116, 16, v87
	v_mul_f32_e32 v65, v117, v117
	ds_write2st64_b32 v246, v96, v97 offset1:8
	v_fmac_f32_e32 v65, v116, v116
	v_lshlrev_b32_e32 v97, 16, v93
	v_lshlrev_b32_e32 v96, 16, v92
	v_and_b32_e32 v93, 0xffff0000, v93
	v_and_b32_e32 v92, 0xffff0000, v92
	v_add_f32_e32 v84, v65, v64
	v_pk_mul_f32 v[64:65], v[92:93], v[92:93]
	v_lshlrev_b32_e32 v99, 16, v95
	v_pk_fma_f32 v[64:65], v[96:97], v[96:97], v[64:65]
	v_lshlrev_b32_e32 v98, 16, v94
	v_add_f32_e32 v64, v64, v84
	v_and_b32_e32 v95, 0xffff0000, v95
	v_and_b32_e32 v94, 0xffff0000, v94
	v_add_f32_e32 v84, v65, v64
	v_pk_mul_f32 v[64:65], v[94:95], v[94:95]
	v_add_u32_e32 v249, 0, v208
	v_pk_fma_f32 v[64:65], v[98:99], v[98:99], v[64:65]
	s_add_i32 s16, s14, 0x30e60000
	v_add_f32_e32 v64, v64, v84
	v_add_f32_e32 v64, v65, v64
	ds_bpermute_b32 v65, v235, v64
	s_waitcnt lgkmcnt(0)
	v_add_f32_e32 v64, v64, v65
	ds_bpermute_b32 v65, v236, v64
	s_waitcnt lgkmcnt(0)
; __device__ __forceinline__ unsigned cvt_pk_bf16(float lo, float hi) { unsigned r; asm volatile("v_cvt_pk_bf16_f32 %0, %1, %2" : "=v"(r) : "v"(lo), "v"(hi)); return r; }
; #define LAS __attribute__((address_space(3)))
; #define MFMA16(a, b, c) __builtin_amdgcn_mfma_f32_16x16x32_bf16((a), (b), (c), 0, 0, 0)
; #define SCHED_FENCE() __builtin_amdgcn_sched_barrier(0)
; #define NA_ISSUE(seq_, slot_) do { _Pragma("unroll") for (int j = 0; j < 4; ++j) st[slot_][j] = bld<u32x4>(R, co, ((seq_) < 8 ? (unsigned)WS_KB + rowb + (unsigned)((seq_) * 131072) : OFF_VT + rowb + (unsigned)(((seq_) - 8) * 131072)) + (unsigned)j * 8192u); } while (0)
; #define NA_WRITE(slot_, buf_) do { _Pragma("unroll") for (int j = 0; j < 4; ++j) *(LAS u32x4*)(lds + (buf_) * NA_BUF + j * 8192 + tid * 16) = st[slot_][j]; } while (0)
; __device__ __forceinline__ void na_attn_block(LAS unsigned char* lds, rsrc_t R, int l, int bx, int G, int tid, int lane, int wave) {
;     ...
;           for (int ks = 0; ks < 4; ++ks) { const f32x4 g0 = gq[ks][0], g1 = gq[ks][1];
;               u32x4 w; w.x = pg8::cvt_pk_bf16(qv[ks][0] * rq * g0[0], qv[ks][1] * rq * g0[1]); w.y = pg8::cvt_pk_bf16(qv[ks][2] * rq * g0[2], qv[ks][3] * rq * g0[3]);
;               w.z = pg8::cvt_pk_bf16(qv[ks][4] * rq * g1[0], qv[ks][5] * rq * g1[1]); w.w = pg8::cvt_pk_bf16(qv[ks][6] * rq * g1[2], qv[ks][7] * rq * g1[3]);
;               qf[ks] = __builtin_bit_cast(bf16x8, w); } }
;         NA_WRITE(0, 0);
;         __syncthreads();
;         f32x4 S[8][2];
; #pragma unroll
;         for (int a = 0; a < 8; ++a) {
;             NA_ISSUE(a + 3, a % 3);
;             SCHED_FENCE();
;             const int buf = (a & 1) * NA_BUF;
; #pragma unroll
;             for (int t = 0; t < 2; ++t) {
;                 f32x4 acc = (f32x4){0.f, 0.f, 0.f, 0.f};
; #pragma unroll
;                 for (int ks = 0; ks < 4; ++ks) { const bf16x8 kf = *(const LAS bf16x8*)(lds + kfb + buf + t * 4096 + ks * 512); acc = MFMA16(kf, qf[ks], acc); }
;                 const f32x4 rk = *(const LAS f32x4*)(lds + skb + a * 512 + t * 64);
;                 S[a][t] = acc * rk;
;             }
;             SCHED_FENCE();
;             NA_WRITE((a + 1) % 3, (a + 1) & 1);
;             __syncthreads();
;         }
	v_add_f32_e32 v64, v64, v65
	v_fmamk_f32 v64, v64, 0x3c000000, v218
	v_rsq_f32_e32 v118, v64
	s_nop 0
	v_mul_f32_e32 v64, v118, v100
	v_mul_f32_e32 v65, v118, v101
	v_mul_f32_e32 v64, v28, v64
	v_mul_f32_e32 v65, v29, v65
	v_cvt_pk_bf16_f32 v84, v64, v65
	v_mul_f32_e32 v64, v118, v102
	v_mul_f32_e32 v65, v118, v103
	v_mul_f32_e32 v64, v30, v64
	v_mul_f32_e32 v65, v31, v65
	v_cvt_pk_bf16_f32 v85, v64, v65
	v_mul_f32_e32 v64, v118, v104
	v_mul_f32_e32 v65, v118, v66
	v_mul_f32_e32 v64, v24, v64
	v_mul_f32_e32 v65, v25, v65
	v_cvt_pk_bf16_f32 v86, v64, v65
	v_mul_f32_e32 v64, v118, v105
	v_mul_f32_e32 v65, v118, v67
	v_mul_f32_e32 v64, v26, v64
	v_mul_f32_e32 v65, v27, v65
	v_cvt_pk_bf16_f32 v87, v64, v65
	v_mul_f32_e32 v64, v118, v106
	v_mul_f32_e32 v65, v118, v68
	v_mul_f32_e32 v64, v20, v64
	v_mul_f32_e32 v65, v21, v65
	v_cvt_pk_bf16_f32 v64, v64, v65
	v_mul_f32_e32 v65, v118, v107
	v_mul_f32_e32 v66, v118, v69
	v_mul_f32_e32 v65, v22, v65
	v_mul_f32_e32 v66, v23, v66
	v_cvt_pk_bf16_f32 v65, v65, v66
	v_mul_f32_e32 v66, v118, v108
	v_mul_f32_e32 v67, v118, v70
	v_mul_f32_e32 v66, v16, v66
	v_mul_f32_e32 v67, v17, v67
	v_cvt_pk_bf16_f32 v66, v66, v67
	v_mul_f32_e32 v67, v118, v109
	v_mul_f32_e32 v68, v118, v71
	v_mul_f32_e32 v67, v18, v67
	v_mul_f32_e32 v68, v19, v68
	v_cvt_pk_bf16_f32 v67, v67, v68
	v_mul_f32_e32 v68, v118, v110
	v_mul_f32_e32 v69, v118, v111
	v_mul_f32_e32 v68, v12, v68
	v_mul_f32_e32 v69, v13, v69
	v_cvt_pk_bf16_f32 v68, v68, v69
	v_mul_f32_e32 v69, v118, v112
	v_mul_f32_e32 v70, v118, v113
	v_mul_f32_e32 v69, v14, v69
	v_mul_f32_e32 v70, v15, v70
	v_cvt_pk_bf16_f32 v69, v69, v70
	v_mul_f32_e32 v70, v118, v114
	v_mul_f32_e32 v71, v118, v115
	v_mul_f32_e32 v70, v8, v70
	v_mul_f32_e32 v71, v9, v71
	v_cvt_pk_bf16_f32 v70, v70, v71
	v_mul_f32_e32 v71, v118, v116
	v_mul_f32_e32 v92, v118, v92
	v_mul_f32_e32 v71, v10, v71
	v_mul_f32_e32 v100, v118, v117
	v_mul_f32_e32 v96, v118, v96
	v_mul_f32_e32 v92, v5, v92
	v_mul_f32_e32 v100, v11, v100
	v_cvt_pk_bf16_f32 v71, v71, v100
	v_mul_f32_e32 v96, v4, v96
	v_cvt_pk_bf16_f32 v104, v96, v92
	v_mul_f32_e32 v92, v118, v97
	v_mul_f32_e32 v93, v118, v93
	v_mul_f32_e32 v92, v6, v92
	v_mul_f32_e32 v93, v7, v93
	v_cvt_pk_bf16_f32 v105, v92, v93
	v_mul_f32_e32 v92, v118, v98
	v_mul_f32_e32 v93, v118, v94
	v_mul_f32_e32 v92, v0, v92
	v_mul_f32_e32 v93, v1, v93
	v_cvt_pk_bf16_f32 v106, v92, v93
	v_mul_f32_e32 v92, v118, v99
	v_mul_f32_e32 v93, v118, v95
	v_mul_f32_e32 v92, v2, v92
	v_mul_f32_e32 v93, v3, v93
	v_cvt_pk_bf16_f32 v107, v92, v93
	ds_write_b128 v249, v[72:75]
	ds_write_b128 v249, v[76:79] offset:8192
	ds_write_b128 v249, v[80:83] offset:16384
	ds_write_b128 v249, v[88:91] offset:24576
	s_waitcnt lgkmcnt(0)
	s_barrier
	ds_write_b128 v249, v[48:51] offset:32768
	ds_write_b128 v249, v[52:55] offset:40960
	ds_write_b128 v249, v[56:59] offset:49152
	ds_write_b128 v249, v[60:63] offset:57344
	buffer_load_dwordx4 v[72:75], v208, s[40:43], s16 offen
	s_add_i32 s16, s14, 0x30e62000
	buffer_load_dwordx4 v[76:79], v208, s[40:43], s16 offen
	s_add_i32 s16, s14, 0x30e64000
	buffer_load_dwordx4 v[80:83], v208, s[40:43], s16 offen
	s_add_i32 s16, s14, 0x30e66000
	buffer_load_dwordx4 v[88:91], v208, s[40:43], s16 offen
	s_nop 0
	s_nop 7
	ds_read_b128 v[210:213], v247
	ds_read_b128 v[224:227], v247 offset:512
	ds_read_b128 v[184:187], v248 offset:64
	ds_read_b128 v[228:231], v247 offset:1024
	ds_read_b128 v[96:99], v248
	s_waitcnt lgkmcnt(4)
	v_mfma_f32_16x16x32_bf16 v[92:95], v[210:213], v[84:87], 0
	ds_read_b128 v[210:213], v247 offset:1536
	s_waitcnt lgkmcnt(4)
	v_mfma_f32_16x16x32_bf16 v[92:95], v[224:227], v[64:67], v[92:95]
	ds_read_b128 v[224:227], v247 offset:4096
	s_waitcnt lgkmcnt(3)
	v_mfma_f32_16x16x32_bf16 v[92:95], v[228:231], v[68:71], v[92:95]
	ds_read_b128 v[228:231], v247 offset:4608
	s_waitcnt lgkmcnt(2)
	v_mfma_f32_16x16x32_bf16 v[92:95], v[210:213], v[104:107], v[92:95]
	ds_read_b128 v[210:213], v247 offset:5120
	s_nop 6
	v_pk_mul_f32 v[214:215], v[94:95], v[98:99]
	v_pk_mul_f32 v[216:217], v[92:93], v[96:97]
	s_waitcnt lgkmcnt(2)
	v_mfma_f32_16x16x32_bf16 v[92:95], v[224:227], v[84:87], 0
	ds_read_b128 v[224:227], v247 offset:5632
	s_waitcnt lgkmcnt(2)
	v_mfma_f32_16x16x32_bf16 v[92:95], v[228:231], v[64:67], v[92:95]
	s_waitcnt lgkmcnt(1)
	v_mfma_f32_16x16x32_bf16 v[92:95], v[210:213], v[68:71], v[92:95]
	s_waitcnt lgkmcnt(0)
	v_mfma_f32_16x16x32_bf16 v[176:179], v[224:227], v[104:107], v[92:95]
	s_nop 7
	s_nop 0
	s_add_i32 s16, s14, 0x30e80000
	s_waitcnt lgkmcnt(0)
	s_barrier
	ds_write_b128 v249, v[32:35]
	ds_write_b128 v249, v[36:39] offset:8192
	ds_write_b128 v249, v[40:43] offset:16384
	ds_write_b128 v249, v[44:47] offset:24576
	buffer_load_dwordx4 v[48:51], v208, s[40:43], s16 offen
	s_add_i32 s16, s14, 0x30e82000
	buffer_load_dwordx4 v[52:55], v208, s[40:43], s16 offen
	s_add_i32 s16, s14, 0x30e84000
	buffer_load_dwordx4 v[56:59], v208, s[40:43], s16 offen
	s_add_i32 s16, s14, 0x30e86000
	buffer_load_dwordx4 v[92:95], v208, s[40:43], s16 offen
	s_nop 0
	s_nop 7
	ds_read_b128 v[210:213], v247 offset:32768
	ds_read_b128 v[224:227], v247 offset:33280
	ds_read_b128 v[228:231], v247 offset:33792
	ds_read_b128 v[168:171], v248 offset:512
	ds_read_b128 v[180:183], v248 offset:576
	s_waitcnt lgkmcnt(4)
	v_mfma_f32_16x16x32_bf16 v[60:63], v[210:213], v[84:87], 0
	ds_read_b128 v[210:213], v247 offset:34304
	s_waitcnt lgkmcnt(4)
	v_mfma_f32_16x16x32_bf16 v[60:63], v[224:227], v[64:67], v[60:63]
	ds_read_b128 v[224:227], v247 offset:36864
	s_waitcnt lgkmcnt(4)
	v_mfma_f32_16x16x32_bf16 v[60:63], v[228:231], v[68:71], v[60:63]
	ds_read_b128 v[228:231], v247 offset:37376
	s_waitcnt lgkmcnt(2)
	v_mfma_f32_16x16x32_bf16 v[164:167], v[210:213], v[104:107], v[60:63]
	ds_read_b128 v[210:213], v247 offset:37888
	s_waitcnt lgkmcnt(2)
	v_mfma_f32_16x16x32_bf16 v[60:63], v[224:227], v[84:87], 0
	ds_read_b128 v[224:227], v247 offset:38400
	s_waitcnt lgkmcnt(2)
	v_mfma_f32_16x16x32_bf16 v[60:63], v[228:231], v[64:67], v[60:63]
	s_waitcnt lgkmcnt(1)
	v_mfma_f32_16x16x32_bf16 v[60:63], v[210:213], v[68:71], v[60:63]
	s_waitcnt lgkmcnt(0)
	v_mfma_f32_16x16x32_bf16 v[172:175], v[224:227], v[104:107], v[60:63]
	s_nop 7
	s_nop 0
	s_add_i32 s16, s14, 0x30ea0000
	s_waitcnt lgkmcnt(0)
	s_barrier
; #define LAS __attribute__((address_space(3)))
; #define MFMA16(a, b, c) __builtin_amdgcn_mfma_f32_16x16x32_bf16((a), (b), (c), 0, 0, 0)
; #define SCHED_FENCE() __builtin_amdgcn_sched_barrier(0)
; #define NA_ISSUE(seq_, slot_) do { _Pragma("unroll") for (int j = 0; j < 4; ++j) st[slot_][j] = bld<u32x4>(R, co, ((seq_) < 8 ? (unsigned)WS_KB + rowb + (unsigned)((seq_) * 131072) : OFF_VT + rowb + (unsigned)(((seq_) - 8) * 131072)) + (unsigned)j * 8192u); } while (0)
; #define NA_WRITE(slot_, buf_) do { _Pragma("unroll") for (int j = 0; j < 4; ++j) *(LAS u32x4*)(lds + (buf_) * NA_BUF + j * 8192 + tid * 16) = st[slot_][j]; } while (0)
; __device__ __forceinline__ void na_attn_block(LAS unsigned char* lds, rsrc_t R, int l, int bx, int G, int tid, int lane, int wave) {
;     ...
; #pragma unroll
;         for (int a = 0; a < 8; ++a) {
;             NA_ISSUE(a + 3, a % 3);
;             SCHED_FENCE();
;             const int buf = (a & 1) * NA_BUF;
; #pragma unroll
;             for (int t = 0; t < 2; ++t) {
;                 f32x4 acc = (f32x4){0.f, 0.f, 0.f, 0.f};
; #pragma unroll
;                 for (int ks = 0; ks < 4; ++ks) { const bf16x8 kf = *(const LAS bf16x8*)(lds + kfb + buf + t * 4096 + ks * 512); acc = MFMA16(kf, qf[ks], acc); }
;                 const f32x4 rk = *(const LAS f32x4*)(lds + skb + a * 512 + t * 64);
;                 S[a][t] = acc * rk;
;             }
;             SCHED_FENCE();
;             NA_WRITE((a + 1) % 3, (a + 1) & 1);
;             __syncthreads();
;         }
	s_waitcnt vmcnt(7)
	ds_write_b128 v249, v[72:75] offset:32768
	s_waitcnt vmcnt(6)
	ds_write_b128 v249, v[76:79] offset:40960
	s_waitcnt vmcnt(5)
	ds_write_b128 v249, v[80:83] offset:49152
	s_waitcnt vmcnt(4)
	ds_write_b128 v249, v[88:91] offset:57344
	buffer_load_dwordx4 v[32:35], v208, s[40:43], s16 offen
	s_add_i32 s16, s14, 0x30ea2000
	buffer_load_dwordx4 v[40:43], v208, s[40:43], s16 offen
	s_add_i32 s16, s14, 0x30ea4000
	buffer_load_dwordx4 v[60:63], v208, s[40:43], s16 offen
	s_add_i32 s16, s14, 0x30ea6000
	buffer_load_dwordx4 v[96:99], v208, s[40:43], s16 offen
	s_nop 0
	s_nop 7
	ds_read_b128 v[210:213], v247
	ds_read_b128 v[224:227], v247 offset:512
	ds_read_b128 v[228:231], v247 offset:1024
	ds_read_b128 v[152:155], v248 offset:1024
	ds_read_b128 v[160:163], v248 offset:1088
	s_waitcnt lgkmcnt(4)
	v_mfma_f32_16x16x32_bf16 v[36:39], v[210:213], v[84:87], 0
	ds_read_b128 v[210:213], v247 offset:1536
	s_waitcnt lgkmcnt(4)
	v_mfma_f32_16x16x32_bf16 v[36:39], v[224:227], v[64:67], v[36:39]
	ds_read_b128 v[224:227], v247 offset:4096
	s_waitcnt lgkmcnt(4)
	v_mfma_f32_16x16x32_bf16 v[36:39], v[228:231], v[68:71], v[36:39]
	ds_read_b128 v[228:231], v247 offset:4608
	s_waitcnt lgkmcnt(2)
	v_mfma_f32_16x16x32_bf16 v[148:151], v[210:213], v[104:107], v[36:39]
	ds_read_b128 v[210:213], v247 offset:5120
	s_waitcnt lgkmcnt(2)
	v_mfma_f32_16x16x32_bf16 v[36:39], v[224:227], v[84:87], 0
	ds_read_b128 v[224:227], v247 offset:5632
	s_waitcnt lgkmcnt(2)
	v_mfma_f32_16x16x32_bf16 v[36:39], v[228:231], v[64:67], v[36:39]
	s_waitcnt lgkmcnt(1)
	v_mfma_f32_16x16x32_bf16 v[36:39], v[210:213], v[68:71], v[36:39]
	s_waitcnt lgkmcnt(0)
	v_mfma_f32_16x16x32_bf16 v[156:159], v[224:227], v[104:107], v[36:39]
	s_nop 7
	s_nop 0
	s_add_i32 s16, s14, 0x30ec0000
	s_waitcnt lgkmcnt(0)
	s_barrier
	s_waitcnt vmcnt(7)
	ds_write_b128 v249, v[48:51]
	s_waitcnt vmcnt(6)
	ds_write_b128 v249, v[52:55] offset:8192
	s_waitcnt vmcnt(5)
	ds_write_b128 v249, v[56:59] offset:16384
	s_waitcnt vmcnt(4)
	ds_write_b128 v249, v[92:95] offset:24576
	buffer_load_dwordx4 v[36:39], v208, s[40:43], s16 offen
	s_add_i32 s16, s14, 0x30ec2000
	buffer_load_dwordx4 v[44:47], v208, s[40:43], s16 offen
	s_add_i32 s16, s14, 0x30ec4000
	buffer_load_dwordx4 v[72:75], v208, s[40:43], s16 offen
	s_add_i32 s16, s14, 0x30ec6000
	buffer_load_dwordx4 v[76:79], v208, s[40:43], s16 offen
	s_nop 0
	s_nop 7
	ds_read_b128 v[210:213], v247 offset:32768
	ds_read_b128 v[224:227], v247 offset:33280
	ds_read_b128 v[228:231], v247 offset:33792
	ds_read_b128 v[132:135], v248 offset:1536
	ds_read_b128 v[144:147], v248 offset:1600
	s_waitcnt lgkmcnt(4)
	v_mfma_f32_16x16x32_bf16 v[80:83], v[210:213], v[84:87], 0
	ds_read_b128 v[210:213], v247 offset:34304
	s_waitcnt lgkmcnt(4)
	v_mfma_f32_16x16x32_bf16 v[80:83], v[224:227], v[64:67], v[80:83]
	ds_read_b128 v[224:227], v247 offset:36864
	s_waitcnt lgkmcnt(4)
	v_mfma_f32_16x16x32_bf16 v[80:83], v[228:231], v[68:71], v[80:83]
	ds_read_b128 v[228:231], v247 offset:37376
	s_waitcnt lgkmcnt(2)
	v_mfma_f32_16x16x32_bf16 v[128:131], v[210:213], v[104:107], v[80:83]
	ds_read_b128 v[210:213], v247 offset:37888
	s_waitcnt lgkmcnt(2)
	v_mfma_f32_16x16x32_bf16 v[80:83], v[224:227], v[84:87], 0
	ds_read_b128 v[224:227], v247 offset:38400
	s_waitcnt lgkmcnt(2)
	v_mfma_f32_16x16x32_bf16 v[80:83], v[228:231], v[64:67], v[80:83]
	s_waitcnt lgkmcnt(1)
	v_mfma_f32_16x16x32_bf16 v[80:83], v[210:213], v[68:71], v[80:83]
	s_waitcnt lgkmcnt(0)
	v_mfma_f32_16x16x32_bf16 v[136:139], v[224:227], v[104:107], v[80:83]
	s_nop 7
	s_nop 0
	s_add_i32 s16, s14, 0x30ee0000
	s_waitcnt lgkmcnt(0)
	s_barrier
	s_waitcnt vmcnt(7)
	ds_write_b128 v249, v[32:35] offset:32768
	s_waitcnt vmcnt(6)
	ds_write_b128 v249, v[40:43] offset:40960
	s_waitcnt vmcnt(5)
	ds_write_b128 v249, v[60:63] offset:49152
	s_waitcnt vmcnt(4)
	ds_write_b128 v249, v[96:99] offset:57344
	buffer_load_dwordx4 v[48:51], v208, s[40:43], s16 offen
	s_add_i32 s16, s14, 0x30ee2000
	buffer_load_dwordx4 v[52:55], v208, s[40:43], s16 offen
	s_add_i32 s16, s14, 0x30ee4000
	buffer_load_dwordx4 v[140:143], v208, s[40:43], s16 offen
	s_add_i32 s16, s14, 0x30ee6000
	buffer_load_dwordx4 v[192:195], v208, s[40:43], s16 offen
	s_nop 0
	s_nop 7
	ds_read_b128 v[210:213], v247
	ds_read_b128 v[224:227], v247 offset:512
	ds_read_b128 v[228:231], v247 offset:1024
	ds_read_b128 v[120:123], v248 offset:2048
	ds_read_b128 v[124:127], v248 offset:2112
	s_waitcnt lgkmcnt(4)
	v_mfma_f32_16x16x32_bf16 v[56:59], v[210:213], v[84:87], 0
	ds_read_b128 v[210:213], v247 offset:1536
	s_waitcnt lgkmcnt(4)
	v_mfma_f32_16x16x32_bf16 v[56:59], v[224:227], v[64:67], v[56:59]
	ds_read_b128 v[224:227], v247 offset:4096
	s_waitcnt lgkmcnt(4)
	v_mfma_f32_16x16x32_bf16 v[56:59], v[228:231], v[68:71], v[56:59]
	ds_read_b128 v[228:231], v247 offset:4608
	s_waitcnt lgkmcnt(2)
	v_mfma_f32_16x16x32_bf16 v[116:119], v[210:213], v[104:107], v[56:59]
	ds_read_b128 v[210:213], v247 offset:5120
	s_waitcnt lgkmcnt(2)
	v_mfma_f32_16x16x32_bf16 v[56:59], v[224:227], v[84:87], 0
	ds_read_b128 v[224:227], v247 offset:5632
	s_waitcnt lgkmcnt(2)
	v_mfma_f32_16x16x32_bf16 v[56:59], v[228:231], v[64:67], v[56:59]
	s_waitcnt lgkmcnt(1)
	v_mfma_f32_16x16x32_bf16 v[56:59], v[210:213], v[68:71], v[56:59]
	s_waitcnt lgkmcnt(0)
	v_mfma_f32_16x16x32_bf16 v[112:115], v[224:227], v[104:107], v[56:59]
	s_nop 7
	s_nop 0
	s_add_i32 s16, s14, 0x20e00000
	s_waitcnt lgkmcnt(0)
	s_barrier
; #define LAS __attribute__((address_space(3)))
; #define MFMA16(a, b, c) __builtin_amdgcn_mfma_f32_16x16x32_bf16((a), (b), (c), 0, 0, 0)
; #define SCHED_FENCE() __builtin_amdgcn_sched_barrier(0)
; #define NA_ISSUE(seq_, slot_) do { _Pragma("unroll") for (int j = 0; j < 4; ++j) st[slot_][j] = bld<u32x4>(R, co, ((seq_) < 8 ? (unsigned)WS_KB + rowb + (unsigned)((seq_) * 131072) : OFF_VT + rowb + (unsigned)(((seq_) - 8) * 131072)) + (unsigned)j * 8192u); } while (0)
; #define NA_WRITE(slot_, buf_) do { _Pragma("unroll") for (int j = 0; j < 4; ++j) *(LAS u32x4*)(lds + (buf_) * NA_BUF + j * 8192 + tid * 16) = st[slot_][j]; } while (0)
; __device__ __forceinline__ void na_attn_block(LAS unsigned char* lds, rsrc_t R, int l, int bx, int G, int tid, int lane, int wave) {
;     ...
; #pragma unroll
;         for (int a = 0; a < 8; ++a) {
;             NA_ISSUE(a + 3, a % 3);
;             SCHED_FENCE();
;             const int buf = (a & 1) * NA_BUF;
; #pragma unroll
;             for (int t = 0; t < 2; ++t) {
;                 f32x4 acc = (f32x4){0.f, 0.f, 0.f, 0.f};
; #pragma unroll
;                 for (int ks = 0; ks < 4; ++ks) { const bf16x8 kf = *(const LAS bf16x8*)(lds + kfb + buf + t * 4096 + ks * 512); acc = MFMA16(kf, qf[ks], acc); }
;                 const f32x4 rk = *(const LAS f32x4*)(lds + skb + a * 512 + t * 64);
;                 S[a][t] = acc * rk;
;             }
;             SCHED_FENCE();
;             NA_WRITE((a + 1) % 3, (a + 1) & 1);
;             __syncthreads();
;         }
;         { const int rowidx0 = start - r + 7;
; #pragma unroll
;           for (int a = 0; a < 8; ++a)
; #pragma unroll
;               for (int q = 0; q < 8; ++q) { const int kcol = kc0 + 16 * (q >> 2) + 4 * kq + (q & 3); const bool valid = (kcol >= cs) && (kcol < cs + 16);
;                   int ci = kcol - qcol + 15; ci = ci < 0 ? 0 : (ci > 30 ? 30 : ci);
;                   const float bias = *(const LAS float*)(lds + NA_RPB + ((h * 15 + rowidx0 + a) * 31 + ci) * 4);
	s_waitcnt vmcnt(7)
	ds_write_b128 v249, v[36:39]
	s_waitcnt vmcnt(6)
	ds_write_b128 v249, v[44:47] offset:8192
	s_waitcnt vmcnt(5)
	ds_write_b128 v249, v[72:75] offset:16384
	s_waitcnt vmcnt(4)
	ds_write_b128 v249, v[76:79] offset:24576
	buffer_load_dwordx4 v[188:191], v208, s[40:43], s16 offen
	s_add_i32 s16, s14, 0x20e02000
	buffer_load_dwordx4 v[196:199], v208, s[40:43], s16 offen
	s_add_i32 s16, s14, 0x20e04000
	buffer_load_dwordx4 v[200:203], v208, s[40:43], s16 offen
	s_add_i32 s16, s14, 0x20e06000
	buffer_load_dwordx4 v[204:207], v208, s[40:43], s16 offen
	s_nop 0
	s_nop 7
	ds_read_b128 v[210:213], v247 offset:32768
	ds_read_b128 v[224:227], v247 offset:33280
	ds_read_b128 v[228:231], v247 offset:33792
	ds_read_b128 v[96:99], v248 offset:2560
	ds_read_b128 v[108:111], v248 offset:2624
	s_waitcnt lgkmcnt(4)
	v_mfma_f32_16x16x32_bf16 v[32:35], v[210:213], v[84:87], 0
	ds_read_b128 v[210:213], v247 offset:34304
	s_waitcnt lgkmcnt(4)
	v_mfma_f32_16x16x32_bf16 v[32:35], v[224:227], v[64:67], v[32:35]
	ds_read_b128 v[224:227], v247 offset:36864
	s_waitcnt lgkmcnt(4)
	v_mfma_f32_16x16x32_bf16 v[32:35], v[228:231], v[68:71], v[32:35]
	ds_read_b128 v[228:231], v247 offset:37376
	s_waitcnt lgkmcnt(2)
	v_mfma_f32_16x16x32_bf16 v[92:95], v[210:213], v[104:107], v[32:35]
	ds_read_b128 v[210:213], v247 offset:37888
	s_waitcnt lgkmcnt(2)
	v_mfma_f32_16x16x32_bf16 v[32:35], v[224:227], v[84:87], 0
	ds_read_b128 v[224:227], v247 offset:38400
	s_waitcnt lgkmcnt(2)
	v_mfma_f32_16x16x32_bf16 v[32:35], v[228:231], v[64:67], v[32:35]
	s_waitcnt lgkmcnt(1)
	v_mfma_f32_16x16x32_bf16 v[32:35], v[210:213], v[68:71], v[32:35]
	s_waitcnt lgkmcnt(0)
	v_mfma_f32_16x16x32_bf16 v[100:103], v[224:227], v[104:107], v[32:35]
	s_nop 7
	s_nop 0
	s_add_i32 s16, s14, 0x20e20000
	s_waitcnt lgkmcnt(0)
	s_barrier
	s_waitcnt vmcnt(7)
	ds_write_b128 v249, v[48:51] offset:32768
	s_waitcnt vmcnt(6)
	ds_write_b128 v249, v[52:55] offset:40960
	s_waitcnt vmcnt(5)
	ds_write_b128 v249, v[140:143] offset:49152
	s_waitcnt vmcnt(4)
	ds_write_b128 v249, v[192:195] offset:57344
	buffer_load_dwordx4 v[32:35], v208, s[40:43], s16 offen
	s_add_i32 s16, s14, 0x20e22000
	buffer_load_dwordx4 v[40:43], v208, s[40:43], s16 offen
	s_add_i32 s16, s14, 0x20e24000
	buffer_load_dwordx4 v[44:47], v208, s[40:43], s16 offen
	s_add_i32 s16, s14, 0x20e26000
	buffer_load_dwordx4 v[56:59], v208, s[40:43], s16 offen
	s_nop 0
	s_nop 7
	ds_read_b128 v[210:213], v247
	ds_read_b128 v[224:227], v247 offset:512
	ds_read_b128 v[228:231], v247 offset:1024
	ds_read_b128 v[76:79], v248 offset:3072
	ds_read_b128 v[88:91], v248 offset:3136
	s_waitcnt lgkmcnt(4)
	v_mfma_f32_16x16x32_bf16 v[36:39], v[210:213], v[84:87], 0
	ds_read_b128 v[210:213], v247 offset:1536
	s_waitcnt lgkmcnt(4)
	v_mfma_f32_16x16x32_bf16 v[36:39], v[224:227], v[64:67], v[36:39]
	ds_read_b128 v[224:227], v247 offset:4096
	s_waitcnt lgkmcnt(4)
	v_mfma_f32_16x16x32_bf16 v[36:39], v[228:231], v[68:71], v[36:39]
	ds_read_b128 v[228:231], v247 offset:4608
	s_waitcnt lgkmcnt(2)
	v_mfma_f32_16x16x32_bf16 v[72:75], v[210:213], v[104:107], v[36:39]
	ds_read_b128 v[210:213], v247 offset:5120
	s_waitcnt lgkmcnt(2)
	v_mfma_f32_16x16x32_bf16 v[36:39], v[224:227], v[84:87], 0
	ds_read_b128 v[224:227], v247 offset:5632
	s_waitcnt lgkmcnt(2)
	v_mfma_f32_16x16x32_bf16 v[36:39], v[228:231], v[64:67], v[36:39]
	s_waitcnt lgkmcnt(1)
	v_mfma_f32_16x16x32_bf16 v[36:39], v[210:213], v[68:71], v[36:39]
	s_waitcnt lgkmcnt(0)
	v_mfma_f32_16x16x32_bf16 v[80:83], v[224:227], v[104:107], v[36:39]
	s_nop 7
	s_nop 0
	s_add_i32 s16, s14, 0x20e40000
	s_waitcnt lgkmcnt(0)
	s_barrier
	s_waitcnt vmcnt(7)
	ds_write_b128 v249, v[188:191]
	s_waitcnt vmcnt(6)
	ds_write_b128 v249, v[196:199] offset:8192
	s_waitcnt vmcnt(5)
	ds_write_b128 v249, v[200:203] offset:16384
	s_waitcnt vmcnt(4)
	ds_write_b128 v249, v[204:207] offset:24576
	buffer_load_dwordx4 v[36:39], v208, s[40:43], s16 offen
	s_add_i32 s16, s14, 0x20e42000
	buffer_load_dwordx4 v[48:51], v208, s[40:43], s16 offen
	s_add_i32 s16, s14, 0x20e44000
	buffer_load_dwordx4 v[52:55], v208, s[40:43], s16 offen
	s_add_i32 s16, s14, 0x20e46000
	buffer_load_dwordx4 v[60:63], v208, s[40:43], s16 offen
	s_nop 0
	s_nop 7
	ds_read_b128 v[210:213], v247 offset:32768
	ds_read_b128 v[224:227], v247 offset:36864
	ds_read_b128 v[228:231], v247 offset:33280
	s_waitcnt lgkmcnt(2)
	v_mfma_f32_16x16x32_bf16 v[140:143], v[210:213], v[84:87], 0
	ds_read_b128 v[210:213], v247 offset:33792
	s_waitcnt lgkmcnt(2)
	v_mfma_f32_16x16x32_bf16 v[192:195], v[224:227], v[84:87], 0
	ds_read_b128 v[224:227], v247 offset:34304
	s_waitcnt lgkmcnt(2)
	v_mfma_f32_16x16x32_bf16 v[84:87], v[228:231], v[64:67], v[140:143]
	ds_read_b128 v[228:231], v247 offset:37376
	s_nop 0
	ds_read_b128 v[140:143], v248 offset:3584
	s_waitcnt lgkmcnt(3)
	v_mfma_f32_16x16x32_bf16 v[84:87], v[210:213], v[68:71], v[84:87]
	ds_read_b128 v[210:213], v247 offset:37888
	s_waitcnt lgkmcnt(3)
	v_mfma_f32_16x16x32_bf16 v[84:87], v[224:227], v[104:107], v[84:87]
	ds_read_b128 v[224:227], v247 offset:38400
	s_waitcnt lgkmcnt(3)
	v_mfma_f32_16x16x32_bf16 v[64:67], v[228:231], v[64:67], v[192:195]
	s_waitcnt lgkmcnt(1)
	v_mfma_f32_16x16x32_bf16 v[68:71], v[210:213], v[68:71], v[64:67]
	s_nop 5
	ds_read_b128 v[64:67], v248 offset:3648
	s_waitcnt lgkmcnt(1)
	v_mfma_f32_16x16x32_bf16 v[68:71], v[224:227], v[104:107], v[68:71]
	s_waitcnt lgkmcnt(0)
	s_nop 6
	s_nop 0
	s_mul_i32 s3, s3, 15
	s_sub_i32 s16, s3, s2
	s_add_i32 s16, s16, 7
	s_add_i32 s15, s16, s15
	s_mul_i32 s15, s15, 31
	s_add_i32 s17, s15, 15
	v_mov_b32_e32 v188, 0xf149f2ca
	v_mov_b32_e32 v189, 0xf149f2ca
	s_waitcnt lgkmcnt(0)
	s_barrier
; #define LAS __attribute__((address_space(3)))
; __device__ __forceinline__ void na_attn_block(LAS unsigned char* lds, rsrc_t R, int l, int bx, int G, int tid, int lane, int wave) {
;     ...
;         { const int rowidx0 = start - r + 7;
; #pragma unroll
;           for (int a = 0; a < 8; ++a)
; #pragma unroll
;               for (int q = 0; q < 8; ++q) { const int kcol = kc0 + 16 * (q >> 2) + 4 * kq + (q & 3); const bool valid = (kcol >= cs) && (kcol < cs + 16);
;                   int ci = kcol - qcol + 15; ci = ci < 0 ? 0 : (ci > 30 ? 30 : ci);
;                   const float bias = *(const LAS float*)(lds + NA_RPB + ((h * 15 + rowidx0 + a) * 31 + ci) * 4);
;                   S[a][q >> 2][q & 3] = valid ? S[a][q >> 2][q & 3] + bias : -1e30f; } }
	v_add_u32_e32 v210, s17, v238
	v_lshl_add_u32 v210, v210, 2, 0
	v_add_u32_e32 v210, 0x11000, v210
	ds_read_b32 v210, v210
	v_add_u32_e32 v211, s17, v239
	v_lshl_add_u32 v211, v211, 2, 0
	v_add_u32_e32 v211, 0x11000, v211
	ds_read_b32 v211, v211
	v_add_u32_e32 v212, s17, v240
	v_lshl_add_u32 v212, v212, 2, 0
	v_add_u32_e32 v212, 0x11000, v212
	ds_read_b32 v212, v212
	v_add_u32_e32 v213, s17, v241
	v_lshl_add_u32 v213, v213, 2, 0
	v_add_u32_e32 v213, 0x11000, v213
	ds_read_b32 v213, v213
	v_add_u32_e32 v224, s17, v242
	v_lshl_add_u32 v224, v224, 2, 0
	v_add_u32_e32 v224, 0x11000, v224
	ds_read_b32 v224, v224
	v_add_u32_e32 v225, s17, v243
	v_lshl_add_u32 v225, v225, 2, 0
	v_add_u32_e32 v225, 0x11000, v225
	ds_read_b32 v225, v225
	v_add_u32_e32 v226, s17, v244
	v_lshl_add_u32 v226, v226, 2, 0
	v_add_u32_e32 v226, 0x11000, v226
	ds_read_b32 v226, v226
	v_add_u32_e32 v227, s17, v245
	v_lshl_add_u32 v227, v227, 2, 0
	v_add_u32_e32 v227, 0x11000, v227
	ds_read_b32 v227, v227
	s_waitcnt lgkmcnt(7)
	v_add_f32_e32 v210, v216, v210
	v_cndmask_b32_e64 v189, v189, v210, s[6:7]
	s_waitcnt lgkmcnt(6)
	v_add_f32_e32 v211, v217, v211
	v_cndmask_b32_e64 v188, v188, v211, s[22:23]
	v_mov_b32_e32 v190, 0xf149f2ca
	v_mov_b32_e32 v191, 0xf149f2ca
	s_waitcnt lgkmcnt(5)
	v_add_f32_e32 v212, v214, v212
	v_cndmask_b32_e64 v191, v191, v212, s[28:29]
	s_waitcnt lgkmcnt(4)
	v_add_f32_e32 v213, v215, v213
	v_cndmask_b32_e64 v190, v190, v213, s[30:31]
	v_pk_mul_f32 v[104:105], v[178:179], v[186:187]
	v_pk_mul_f32 v[106:107], v[176:177], v[184:185]
	v_mov_b32_e32 v176, 0xf149f2ca
	v_mov_b32_e32 v177, 0xf149f2ca
	s_waitcnt lgkmcnt(3)
	v_add_f32_e32 v224, v106, v224
	v_cndmask_b32_e64 v177, v177, v224, s[36:37]
	s_waitcnt lgkmcnt(2)
	v_add_f32_e32 v225, v107, v225
	v_cndmask_b32_e64 v176, v176, v225, s[38:39]
	v_mov_b32_e32 v178, 0xf149f2ca
	v_mov_b32_e32 v179, 0xf149f2ca
	s_waitcnt lgkmcnt(1)
	v_add_f32_e32 v226, v104, v226
	v_cndmask_b32_e64 v179, v179, v226, s[44:45]
	s_waitcnt lgkmcnt(0)
	v_add_f32_e32 v227, v105, v227
	v_cndmask_b32_e64 v178, v178, v227, s[0:1]
	v_pk_mul_f32 v[104:105], v[166:167], v[170:171]
	v_pk_mul_f32 v[106:107], v[164:165], v[168:169]
	s_add_i32 s17, s15, 46
	v_mov_b32_e32 v164, 0xf149f2ca
	v_mov_b32_e32 v165, 0xf149f2ca
	v_add_u32_e32 v210, s17, v238
	v_lshl_add_u32 v210, v210, 2, 0
	v_add_u32_e32 v210, 0x11000, v210
	ds_read_b32 v210, v210
	v_add_u32_e32 v211, s17, v239
	v_lshl_add_u32 v211, v211, 2, 0
	v_add_u32_e32 v211, 0x11000, v211
	ds_read_b32 v211, v211
	v_add_u32_e32 v212, s17, v240
	v_lshl_add_u32 v212, v212, 2, 0
	v_add_u32_e32 v212, 0x11000, v212
	ds_read_b32 v212, v212
	v_add_u32_e32 v213, s17, v241
	v_lshl_add_u32 v213, v213, 2, 0
	v_add_u32_e32 v213, 0x11000, v213
	ds_read_b32 v213, v213
	v_add_u32_e32 v224, s17, v242
	v_lshl_add_u32 v224, v224, 2, 0
	v_add_u32_e32 v224, 0x11000, v224
	ds_read_b32 v224, v224
	v_add_u32_e32 v225, s17, v243
	v_lshl_add_u32 v225, v225, 2, 0
	v_add_u32_e32 v225, 0x11000, v225
	ds_read_b32 v225, v225
	v_add_u32_e32 v226, s17, v244
	v_lshl_add_u32 v226, v226, 2, 0
	v_add_u32_e32 v226, 0x11000, v226
	ds_read_b32 v226, v226
	v_add_u32_e32 v227, s17, v245
	v_lshl_add_u32 v227, v227, 2, 0
	v_add_u32_e32 v227, 0x11000, v227
	ds_read_b32 v227, v227
	s_waitcnt lgkmcnt(7)
	v_add_f32_e32 v210, v106, v210
	v_cndmask_b32_e64 v165, v165, v210, s[6:7]
	s_waitcnt lgkmcnt(6)
	v_add_f32_e32 v211, v107, v211
	v_cndmask_b32_e64 v164, v164, v211, s[22:23]
	v_mov_b32_e32 v166, 0xf149f2ca
	v_mov_b32_e32 v167, 0xf149f2ca
	s_waitcnt lgkmcnt(5)
	v_add_f32_e32 v212, v104, v212
	v_cndmask_b32_e64 v167, v167, v212, s[28:29]
	s_waitcnt lgkmcnt(4)
	v_add_f32_e32 v213, v105, v213
	v_cndmask_b32_e64 v166, v166, v213, s[30:31]
	v_pk_mul_f32 v[104:105], v[174:175], v[182:183]
	v_pk_mul_f32 v[106:107], v[172:173], v[180:181]
	v_mov_b32_e32 v168, 0xf149f2ca
	v_mov_b32_e32 v169, 0xf149f2ca
	s_waitcnt lgkmcnt(3)
	v_add_f32_e32 v224, v106, v224
	v_cndmask_b32_e64 v169, v169, v224, s[36:37]
	s_waitcnt lgkmcnt(2)
	v_add_f32_e32 v225, v107, v225
	v_cndmask_b32_e64 v168, v168, v225, s[38:39]
	v_mov_b32_e32 v170, 0xf149f2ca
	v_mov_b32_e32 v171, 0xf149f2ca
	s_waitcnt lgkmcnt(1)
	v_add_f32_e32 v226, v104, v226
	v_cndmask_b32_e64 v171, v171, v226, s[44:45]
	s_waitcnt lgkmcnt(0)
	v_add_f32_e32 v227, v105, v227
	v_cndmask_b32_e64 v170, v170, v227, s[0:1]
	v_pk_mul_f32 v[104:105], v[150:151], v[154:155]
	v_pk_mul_f32 v[106:107], v[148:149], v[152:153]
	s_add_i32 s17, s15, 0x4d
	v_mov_b32_e32 v148, 0xf149f2ca
	v_mov_b32_e32 v149, 0xf149f2ca
	v_add_u32_e32 v210, s17, v238
	v_lshl_add_u32 v210, v210, 2, 0
	v_add_u32_e32 v210, 0x11000, v210
	ds_read_b32 v210, v210
	v_add_u32_e32 v211, s17, v239
	v_lshl_add_u32 v211, v211, 2, 0
	v_add_u32_e32 v211, 0x11000, v211
	ds_read_b32 v211, v211
	v_add_u32_e32 v212, s17, v240
	v_lshl_add_u32 v212, v212, 2, 0
	v_add_u32_e32 v212, 0x11000, v212
	ds_read_b32 v212, v212
	v_add_u32_e32 v213, s17, v241
	v_lshl_add_u32 v213, v213, 2, 0
	v_add_u32_e32 v213, 0x11000, v213
	ds_read_b32 v213, v213
	v_add_u32_e32 v224, s17, v242
	v_lshl_add_u32 v224, v224, 2, 0
	v_add_u32_e32 v224, 0x11000, v224
	ds_read_b32 v224, v224
	v_add_u32_e32 v225, s17, v243
	v_lshl_add_u32 v225, v225, 2, 0
	v_add_u32_e32 v225, 0x11000, v225
	ds_read_b32 v225, v225
	v_add_u32_e32 v226, s17, v244
	v_lshl_add_u32 v226, v226, 2, 0
	v_add_u32_e32 v226, 0x11000, v226
	ds_read_b32 v226, v226
	v_add_u32_e32 v227, s17, v245
	v_lshl_add_u32 v227, v227, 2, 0
	v_add_u32_e32 v227, 0x11000, v227
	ds_read_b32 v227, v227
	s_waitcnt lgkmcnt(7)
	v_add_f32_e32 v210, v106, v210
	v_cndmask_b32_e64 v149, v149, v210, s[6:7]
	s_waitcnt lgkmcnt(6)
; #define LAS __attribute__((address_space(3)))
; __device__ __forceinline__ void na_attn_block(LAS unsigned char* lds, rsrc_t R, int l, int bx, int G, int tid, int lane, int wave) {
;     ...
;         { const int rowidx0 = start - r + 7;
; #pragma unroll
;           for (int a = 0; a < 8; ++a)
; #pragma unroll
;               for (int q = 0; q < 8; ++q) { const int kcol = kc0 + 16 * (q >> 2) + 4 * kq + (q & 3); const bool valid = (kcol >= cs) && (kcol < cs + 16);
;                   int ci = kcol - qcol + 15; ci = ci < 0 ? 0 : (ci > 30 ? 30 : ci);
;                   const float bias = *(const LAS float*)(lds + NA_RPB + ((h * 15 + rowidx0 + a) * 31 + ci) * 4);
;                   S[a][q >> 2][q & 3] = valid ? S[a][q >> 2][q & 3] + bias : -1e30f; } }
	v_add_f32_e32 v211, v107, v211
	v_cndmask_b32_e64 v148, v148, v211, s[22:23]
	v_mov_b32_e32 v150, 0xf149f2ca
	v_mov_b32_e32 v151, 0xf149f2ca
	s_waitcnt lgkmcnt(5)
	v_add_f32_e32 v212, v104, v212
	v_cndmask_b32_e64 v151, v151, v212, s[28:29]
	s_waitcnt lgkmcnt(4)
	v_add_f32_e32 v213, v105, v213
	v_cndmask_b32_e64 v150, v150, v213, s[30:31]
	v_pk_mul_f32 v[104:105], v[158:159], v[162:163]
	v_pk_mul_f32 v[106:107], v[156:157], v[160:161]
	v_mov_b32_e32 v152, 0xf149f2ca
	v_mov_b32_e32 v153, 0xf149f2ca
	s_waitcnt lgkmcnt(3)
	v_add_f32_e32 v224, v106, v224
	v_cndmask_b32_e64 v153, v153, v224, s[36:37]
	s_waitcnt lgkmcnt(2)
	v_add_f32_e32 v225, v107, v225
	v_cndmask_b32_e64 v152, v152, v225, s[38:39]
	v_mov_b32_e32 v154, 0xf149f2ca
	v_mov_b32_e32 v155, 0xf149f2ca
	s_waitcnt lgkmcnt(1)
	v_add_f32_e32 v226, v104, v226
	v_cndmask_b32_e64 v155, v155, v226, s[44:45]
	s_waitcnt lgkmcnt(0)
	v_add_f32_e32 v227, v105, v227
	v_cndmask_b32_e64 v154, v154, v227, s[0:1]
	v_pk_mul_f32 v[104:105], v[130:131], v[134:135]
	v_pk_mul_f32 v[106:107], v[128:129], v[132:133]
	s_add_i32 s17, s15, 0x6c
	v_mov_b32_e32 v128, 0xf149f2ca
	v_mov_b32_e32 v129, 0xf149f2ca
	v_add_u32_e32 v210, s17, v238
	v_lshl_add_u32 v210, v210, 2, 0
	v_add_u32_e32 v210, 0x11000, v210
	ds_read_b32 v210, v210
	v_add_u32_e32 v211, s17, v239
	v_lshl_add_u32 v211, v211, 2, 0
	v_add_u32_e32 v211, 0x11000, v211
	ds_read_b32 v211, v211
	v_add_u32_e32 v212, s17, v240
	v_lshl_add_u32 v212, v212, 2, 0
	v_add_u32_e32 v212, 0x11000, v212
	ds_read_b32 v212, v212
	v_add_u32_e32 v213, s17, v241
	v_lshl_add_u32 v213, v213, 2, 0
	v_add_u32_e32 v213, 0x11000, v213
	ds_read_b32 v213, v213
	v_add_u32_e32 v224, s17, v242
	v_lshl_add_u32 v224, v224, 2, 0
	v_add_u32_e32 v224, 0x11000, v224
	ds_read_b32 v224, v224
	v_add_u32_e32 v225, s17, v243
	v_lshl_add_u32 v225, v225, 2, 0
	v_add_u32_e32 v225, 0x11000, v225
	ds_read_b32 v225, v225
	v_add_u32_e32 v226, s17, v244
	v_lshl_add_u32 v226, v226, 2, 0
	v_add_u32_e32 v226, 0x11000, v226
	ds_read_b32 v226, v226
	v_add_u32_e32 v227, s17, v245
	v_lshl_add_u32 v227, v227, 2, 0
	v_add_u32_e32 v227, 0x11000, v227
	ds_read_b32 v227, v227
	s_waitcnt lgkmcnt(7)
	v_add_f32_e32 v210, v106, v210
	v_cndmask_b32_e64 v129, v129, v210, s[6:7]
	s_waitcnt lgkmcnt(6)
	v_add_f32_e32 v211, v107, v211
	v_cndmask_b32_e64 v128, v128, v211, s[22:23]
	v_mov_b32_e32 v130, 0xf149f2ca
	v_mov_b32_e32 v131, 0xf149f2ca
	s_waitcnt lgkmcnt(5)
	v_add_f32_e32 v212, v104, v212
	v_cndmask_b32_e64 v131, v131, v212, s[28:29]
	s_waitcnt lgkmcnt(4)
	v_add_f32_e32 v213, v105, v213
	v_cndmask_b32_e64 v130, v130, v213, s[30:31]
	v_pk_mul_f32 v[104:105], v[138:139], v[146:147]
	v_pk_mul_f32 v[106:107], v[136:137], v[144:145]
	v_mov_b32_e32 v132, 0xf149f2ca
	v_mov_b32_e32 v133, 0xf149f2ca
	s_waitcnt lgkmcnt(3)
	v_add_f32_e32 v224, v106, v224
	v_cndmask_b32_e64 v133, v133, v224, s[36:37]
	s_waitcnt lgkmcnt(2)
	v_add_f32_e32 v225, v107, v225
	v_cndmask_b32_e64 v132, v132, v225, s[38:39]
	v_mov_b32_e32 v134, 0xf149f2ca
	v_mov_b32_e32 v135, 0xf149f2ca
	s_waitcnt lgkmcnt(1)
	v_add_f32_e32 v226, v104, v226
	v_cndmask_b32_e64 v135, v135, v226, s[44:45]
	s_waitcnt lgkmcnt(0)
	v_add_f32_e32 v227, v105, v227
	v_cndmask_b32_e64 v134, v134, v227, s[0:1]
	v_pk_mul_f32 v[106:107], v[116:117], v[120:121]
	v_add_u32_e32 v116, s16, v250
	v_mul_lo_u32 v116, v116, 31
	v_pk_mul_f32 v[104:105], v[118:119], v[122:123]
	v_add_u32_e32 v120, 15, v116
	v_mov_b32_e32 v116, 0xf149f2ca
	v_mov_b32_e32 v117, 0xf149f2ca
	v_add_u32_e32 v210, v120, v238
	v_lshl_add_u32 v210, v210, 2, 0
	v_add_u32_e32 v210, 0x11000, v210
	ds_read_b32 v210, v210
	v_add_u32_e32 v211, v120, v239
	v_lshl_add_u32 v211, v211, 2, 0
	v_add_u32_e32 v211, 0x11000, v211
	ds_read_b32 v211, v211
	v_add_u32_e32 v212, v120, v240
	v_lshl_add_u32 v212, v212, 2, 0
	v_add_u32_e32 v212, 0x11000, v212
	ds_read_b32 v212, v212
	v_add_u32_e32 v213, v120, v241
	v_lshl_add_u32 v213, v213, 2, 0
	v_add_u32_e32 v213, 0x11000, v213
	ds_read_b32 v213, v213
	v_add_u32_e32 v224, v120, v242
	v_lshl_add_u32 v224, v224, 2, 0
	v_add_u32_e32 v224, 0x11000, v224
	ds_read_b32 v224, v224
	v_add_u32_e32 v225, v120, v243
	v_lshl_add_u32 v225, v225, 2, 0
	v_add_u32_e32 v225, 0x11000, v225
	ds_read_b32 v225, v225
	v_add_u32_e32 v226, v120, v244
	v_lshl_add_u32 v226, v226, 2, 0
	v_add_u32_e32 v226, 0x11000, v226
	ds_read_b32 v226, v226
	v_add_u32_e32 v227, v120, v245
	v_lshl_add_u32 v227, v227, 2, 0
	v_add_u32_e32 v227, 0x11000, v227
	ds_read_b32 v227, v227
	s_waitcnt lgkmcnt(7)
	v_add_f32_e32 v210, v106, v210
	v_cndmask_b32_e64 v117, v117, v210, s[6:7]
	s_waitcnt lgkmcnt(6)
	v_add_f32_e32 v211, v107, v211
	v_cndmask_b32_e64 v116, v116, v211, s[22:23]
	v_mov_b32_e32 v118, 0xf149f2ca
	v_mov_b32_e32 v119, 0xf149f2ca
	s_waitcnt lgkmcnt(5)
	v_add_f32_e32 v212, v104, v212
	v_cndmask_b32_e64 v119, v119, v212, s[28:29]
	s_waitcnt lgkmcnt(4)
	v_add_f32_e32 v213, v105, v213
	v_cndmask_b32_e64 v118, v118, v213, s[30:31]
	v_pk_mul_f32 v[104:105], v[114:115], v[126:127]
	v_pk_mul_f32 v[106:107], v[112:113], v[124:125]
	v_mov_b32_e32 v112, 0xf149f2ca
	v_mov_b32_e32 v113, 0xf149f2ca
	s_waitcnt lgkmcnt(3)
	v_add_f32_e32 v224, v106, v224
	v_cndmask_b32_e64 v113, v113, v224, s[36:37]
	s_waitcnt lgkmcnt(2)
	v_add_f32_e32 v225, v107, v225
	v_cndmask_b32_e64 v112, v112, v225, s[38:39]
	v_mov_b32_e32 v106, 0xf149f2ca
	v_mov_b32_e32 v107, 0xf149f2ca
	s_waitcnt lgkmcnt(1)
	v_add_f32_e32 v226, v104, v226
	v_cndmask_b32_e64 v107, v107, v226, s[44:45]
	s_waitcnt lgkmcnt(0)
; #define LAS __attribute__((address_space(3)))
; __device__ __forceinline__ void na_attn_block(LAS unsigned char* lds, rsrc_t R, int l, int bx, int G, int tid, int lane, int wave) {
;     ...
;         { const int rowidx0 = start - r + 7;
; #pragma unroll
;           for (int a = 0; a < 8; ++a)
; #pragma unroll
;               for (int q = 0; q < 8; ++q) { const int kcol = kc0 + 16 * (q >> 2) + 4 * kq + (q & 3); const bool valid = (kcol >= cs) && (kcol < cs + 16);
;                   int ci = kcol - qcol + 15; ci = ci < 0 ? 0 : (ci > 30 ? 30 : ci);
;                   const float bias = *(const LAS float*)(lds + NA_RPB + ((h * 15 + rowidx0 + a) * 31 + ci) * 4);
;                   S[a][q >> 2][q & 3] = valid ? S[a][q >> 2][q & 3] + bias : -1e30f; } }
	v_add_f32_e32 v227, v105, v227
	v_cndmask_b32_e64 v106, v106, v227, s[0:1]
	v_pk_mul_f32 v[94:95], v[94:95], v[98:99]
	v_pk_mul_f32 v[92:93], v[92:93], v[96:97]
	s_add_i32 s16, s15, 0xaa
	v_mov_b32_e32 v96, 0xf149f2ca
	v_mov_b32_e32 v97, 0xf149f2ca
	v_add_u32_e32 v210, s16, v238
	v_lshl_add_u32 v210, v210, 2, 0
	v_add_u32_e32 v210, 0x11000, v210
	ds_read_b32 v210, v210
	v_add_u32_e32 v211, s16, v239
	v_lshl_add_u32 v211, v211, 2, 0
	v_add_u32_e32 v211, 0x11000, v211
	ds_read_b32 v211, v211
	v_add_u32_e32 v212, s16, v240
	v_lshl_add_u32 v212, v212, 2, 0
	v_add_u32_e32 v212, 0x11000, v212
	ds_read_b32 v212, v212
	v_add_u32_e32 v213, s16, v241
	v_lshl_add_u32 v213, v213, 2, 0
	v_add_u32_e32 v213, 0x11000, v213
	ds_read_b32 v213, v213
	v_add_u32_e32 v224, s16, v242
	v_lshl_add_u32 v224, v224, 2, 0
	v_add_u32_e32 v224, 0x11000, v224
	ds_read_b32 v224, v224
	v_add_u32_e32 v225, s16, v243
	v_lshl_add_u32 v225, v225, 2, 0
	v_add_u32_e32 v225, 0x11000, v225
	ds_read_b32 v225, v225
	v_add_u32_e32 v226, s16, v244
	v_lshl_add_u32 v226, v226, 2, 0
	v_add_u32_e32 v226, 0x11000, v226
	ds_read_b32 v226, v226
	v_add_u32_e32 v227, s16, v245
	v_lshl_add_u32 v227, v227, 2, 0
	v_add_u32_e32 v227, 0x11000, v227
	ds_read_b32 v227, v227
	s_waitcnt lgkmcnt(7)
	v_add_f32_e32 v210, v92, v210
	v_cndmask_b32_e64 v97, v97, v210, s[6:7]
	s_waitcnt lgkmcnt(6)
	v_add_f32_e32 v211, v93, v211
	v_cndmask_b32_e64 v96, v96, v211, s[22:23]
	v_mov_b32_e32 v98, 0xf149f2ca
	v_mov_b32_e32 v99, 0xf149f2ca
	s_waitcnt lgkmcnt(5)
	v_add_f32_e32 v212, v94, v212
	v_cndmask_b32_e64 v99, v99, v212, s[28:29]
	s_waitcnt lgkmcnt(4)
	v_add_f32_e32 v213, v95, v213
	v_cndmask_b32_e64 v98, v98, v213, s[30:31]
	v_pk_mul_f32 v[92:93], v[102:103], v[110:111]
	v_pk_mul_f32 v[94:95], v[100:101], v[108:109]
	v_mov_b32_e32 v100, 0xf149f2ca
	v_mov_b32_e32 v105, 0xf149f2ca
	s_waitcnt lgkmcnt(3)
	v_add_f32_e32 v224, v94, v224
	v_cndmask_b32_e64 v105, v105, v224, s[36:37]
	s_waitcnt lgkmcnt(2)
	v_add_f32_e32 v225, v95, v225
	v_cndmask_b32_e64 v100, v100, v225, s[38:39]
	v_mov_b32_e32 v94, 0xf149f2ca
	v_mov_b32_e32 v95, 0xf149f2ca
	s_waitcnt lgkmcnt(1)
	v_add_f32_e32 v226, v92, v226
	v_cndmask_b32_e64 v95, v95, v226, s[44:45]
	s_waitcnt lgkmcnt(0)
	v_add_f32_e32 v227, v93, v227
	v_cndmask_b32_e64 v94, v94, v227, s[0:1]
	v_pk_mul_f32 v[74:75], v[74:75], v[78:79]
	v_pk_mul_f32 v[72:73], v[72:73], v[76:77]
	s_add_i32 s16, s15, 0xc9
	v_mov_b32_e32 v76, 0xf149f2ca
	v_mov_b32_e32 v77, 0xf149f2ca
	v_add_u32_e32 v210, s16, v238
	v_lshl_add_u32 v210, v210, 2, 0
	v_add_u32_e32 v210, 0x11000, v210
	ds_read_b32 v210, v210
	v_add_u32_e32 v211, s16, v239
	v_lshl_add_u32 v211, v211, 2, 0
	v_add_u32_e32 v211, 0x11000, v211
	ds_read_b32 v211, v211
	v_add_u32_e32 v212, s16, v240
	v_lshl_add_u32 v212, v212, 2, 0
	v_add_u32_e32 v212, 0x11000, v212
	ds_read_b32 v212, v212
	v_add_u32_e32 v213, s16, v241
	v_lshl_add_u32 v213, v213, 2, 0
	v_add_u32_e32 v213, 0x11000, v213
	ds_read_b32 v213, v213
	v_add_u32_e32 v224, s16, v242
	v_lshl_add_u32 v224, v224, 2, 0
	v_add_u32_e32 v224, 0x11000, v224
	ds_read_b32 v224, v224
	v_add_u32_e32 v225, s16, v243
	v_lshl_add_u32 v225, v225, 2, 0
	v_add_u32_e32 v225, 0x11000, v225
	ds_read_b32 v225, v225
	v_add_u32_e32 v226, s16, v244
	v_lshl_add_u32 v226, v226, 2, 0
	v_add_u32_e32 v226, 0x11000, v226
	ds_read_b32 v226, v226
	v_add_u32_e32 v227, s16, v245
	v_lshl_add_u32 v227, v227, 2, 0
	v_add_u32_e32 v227, 0x11000, v227
	ds_read_b32 v227, v227
	s_waitcnt lgkmcnt(7)
	v_add_f32_e32 v210, v72, v210
	v_cndmask_b32_e64 v77, v77, v210, s[6:7]
	s_waitcnt lgkmcnt(6)
	v_add_f32_e32 v211, v73, v211
	v_cndmask_b32_e64 v76, v76, v211, s[22:23]
	v_mov_b32_e32 v78, 0xf149f2ca
	v_mov_b32_e32 v79, 0xf149f2ca
	s_waitcnt lgkmcnt(5)
	v_add_f32_e32 v212, v74, v212
	v_cndmask_b32_e64 v79, v79, v212, s[28:29]
	s_waitcnt lgkmcnt(4)
	v_add_f32_e32 v213, v75, v213
	v_cndmask_b32_e64 v78, v78, v213, s[30:31]
	v_pk_mul_f32 v[72:73], v[82:83], v[90:91]
	v_pk_mul_f32 v[74:75], v[80:81], v[88:89]
	v_mov_b32_e32 v80, 0xf149f2ca
	v_mov_b32_e32 v81, 0xf149f2ca
	s_waitcnt lgkmcnt(3)
	v_add_f32_e32 v224, v74, v224
	v_cndmask_b32_e64 v81, v81, v224, s[36:37]
	s_waitcnt lgkmcnt(2)
	v_add_f32_e32 v225, v75, v225
	v_cndmask_b32_e64 v80, v80, v225, s[38:39]
	v_mov_b32_e32 v82, 0xf149f2ca
	v_mov_b32_e32 v83, 0xf149f2ca
	s_waitcnt lgkmcnt(1)
	v_add_f32_e32 v226, v72, v226
	v_cndmask_b32_e64 v83, v83, v226, s[44:45]
	s_waitcnt lgkmcnt(0)
	v_add_f32_e32 v227, v73, v227
	v_cndmask_b32_e64 v82, v82, v227, s[0:1]
	v_pk_mul_f32 v[72:73], v[86:87], v[142:143]
	v_pk_mul_f32 v[74:75], v[84:85], v[140:141]
	s_addk_i32 s15, 0xe8
	v_mov_b32_e32 v84, 0xf149f2ca
	v_mov_b32_e32 v85, 0xf149f2ca
	v_add_u32_e32 v210, s15, v238
	v_lshl_add_u32 v210, v210, 2, 0
	v_add_u32_e32 v210, 0x11000, v210
	ds_read_b32 v210, v210
	v_add_u32_e32 v211, s15, v239
	v_lshl_add_u32 v211, v211, 2, 0
	v_add_u32_e32 v211, 0x11000, v211
	ds_read_b32 v211, v211
	v_add_u32_e32 v212, s15, v240
	v_lshl_add_u32 v212, v212, 2, 0
	v_add_u32_e32 v212, 0x11000, v212
	ds_read_b32 v212, v212
	v_add_u32_e32 v213, s15, v241
	v_lshl_add_u32 v213, v213, 2, 0
	v_add_u32_e32 v213, 0x11000, v213
	ds_read_b32 v213, v213
	v_add_u32_e32 v224, s15, v242
	v_lshl_add_u32 v224, v224, 2, 0
	v_add_u32_e32 v224, 0x11000, v224
	ds_read_b32 v224, v224
	v_add_u32_e32 v225, s15, v243
	v_lshl_add_u32 v225, v225, 2, 0
	v_add_u32_e32 v225, 0x11000, v225
	ds_read_b32 v225, v225
	v_add_u32_e32 v226, s15, v244
	v_lshl_add_u32 v226, v226, 2, 0
	v_add_u32_e32 v226, 0x11000, v226
	ds_read_b32 v226, v226
	v_add_u32_e32 v227, s15, v245
	v_lshl_add_u32 v227, v227, 2, 0
	v_add_u32_e32 v227, 0x11000, v227
	ds_read_b32 v227, v227
	s_waitcnt lgkmcnt(7)
	v_add_f32_e32 v210, v74, v210
	v_cndmask_b32_e64 v85, v85, v210, s[6:7]
	s_waitcnt lgkmcnt(6)
	v_add_f32_e32 v211, v75, v211
	v_cndmask_b32_e64 v84, v84, v211, s[22:23]
	v_mov_b32_e32 v74, 0xf149f2ca
	v_mov_b32_e32 v75, 0xf149f2ca
	s_waitcnt lgkmcnt(5)
	v_add_f32_e32 v212, v72, v212
	v_cndmask_b32_e64 v75, v75, v212, s[28:29]
	s_waitcnt lgkmcnt(4)
	v_add_f32_e32 v213, v73, v213
	v_cndmask_b32_e64 v74, v74, v213, s[30:31]
	v_pk_mul_f32 v[66:67], v[70:71], v[66:67]
	v_pk_mul_f32 v[64:65], v[68:69], v[64:65]
	v_mov_b32_e32 v68, 0xf149f2ca
	v_mov_b32_e32 v69, 0xf149f2ca
	s_waitcnt lgkmcnt(3)
	v_add_f32_e32 v224, v64, v224
	v_cndmask_b32_e64 v69, v69, v224, s[36:37]
	s_waitcnt lgkmcnt(2)
	v_add_f32_e32 v225, v65, v225
	v_cndmask_b32_e64 v68, v68, v225, s[38:39]
	v_mov_b32_e32 v64, 0xf149f2ca
	v_mov_b32_e32 v65, 0xf149f2ca
	s_waitcnt lgkmcnt(1)
	v_add_f32_e32 v226, v66, v226
	v_cndmask_b32_e64 v65, v65, v226, s[44:45]
	s_waitcnt lgkmcnt(0)
	v_add_f32_e32 v227, v67, v227
	v_cndmask_b32_e64 v64, v64, v227, s[0:1]
	s_branch .Lna2_184
